# speedup vs baseline: 1.0442x; 1.0185x over previous
; __device__ __forceinline__ void norm_rows(const float* __restrict__ src, const float* __restrict__ g, u16* __restrict__ dst) {
;   const int lane = tid_opaque() & 63;
;   f32x4 v[4];
;   float ss = 0.f;
; #pragma unroll
;   for (int i = 0; i < 4; ++i) {
;     v[i] = *(const f32x4*)(src + i * 256 + lane * 4);
;     ss += v[i].x * v[i].x + v[i].y * v[i].y + v[i].z * v[i].z + v[i].w * v[i].w;
;   }
;   ss = wave_sum(ss);
;   float rstd = rsqrtf(ss * (1.f / 1024.f) + EPS);
; #pragma unroll
;   for (int i = 0; i < 4; ++i) {
;     f32x4 gg = *(const f32x4*)(g + i * 256 + lane * 4);
;     u32x2 o;
;     o.x = pack2(v[i].x * rstd * gg.x, v[i].y * rstd * gg.y);
;     o.y = pack2(v[i].z * rstd * gg.z, v[i].w * rstd * gg.w);
;     *(u32x2*)(dst + i * 256 + lane * 4) = o;
;   }
; }
.LBB0_19:
	s_or_b64 exec, exec, s[4:5]
	v_lshlrev_b64 v[4:5], 11, v[4:5]
	v_lshl_add_u64 v[20:21], s[60:61], 0, v[4:5]
	v_mov_b32_e32 v4, v198
	s_load_dwordx16 s[4:19], s[28:29], 0x40
	v_lshlrev_b32_e32 v4, 2, v4
	v_and_b32_e32 v38, 0xfc, v4
	v_lshlrev_b32_e32 v18, 2, v38
	v_lshl_add_u64 v[2:3], v[2:3], 0, v[18:19]
	global_load_dwordx4 v[14:17], v[2:3], off
	global_load_dwordx4 v[6:9], v[2:3], off offset:1024
	global_load_dwordx4 v[10:13], v[2:3], off offset:2048
	s_nop 0
	global_load_dwordx4 v[2:5], v[2:3], off offset:3072
	s_waitcnt lgkmcnt(0)
	global_load_dwordx4 v[228:231], v18, s[10:11]
	global_load_dwordx4 v[232:235], v18, s[10:11] offset:1024
	global_load_dwordx4 v[236:239], v18, s[10:11] offset:2048
	global_load_dwordx4 v[240:243], v18, s[10:11] offset:3072
	v_cmp_lt_i32_e32 vcc, v30, v29
	v_lshlrev_b32_e32 v24, 1, v38
	v_mov_b32_e32 v25, v19
	v_lshl_add_u64 v[20:21], v[20:21], 0, v[24:25]
	s_waitcnt vmcnt(4)
	v_mov_b32_e32 v200, v15
	v_mov_b32_e32 v201, v7
	v_mov_b32_e32 v202, v14
	v_mov_b32_e32 v203, v6
	v_pk_mul_f32 v[200:201], v[200:201], v[200:201]
	s_nop 0
	v_pk_fma_f32 v[202:203], v[202:203], v[202:203], v[200:201]
	v_mov_b32_e32 v200, v16
	v_mov_b32_e32 v201, v8
	v_pk_fma_f32 v[202:203], v[200:201], v[200:201], v[202:203]
	v_mov_b32_e32 v200, v17
	v_mov_b32_e32 v201, v9
	v_pk_fma_f32 v[22:23], v[200:201], v[200:201], v[202:203]
	s_nop 0
	v_add_f32_e32 v22, v22, v23
	v_cndmask_b32_e32 v23, v28, v30, vcc
	v_lshlrev_b32_e32 v23, 2, v23
	v_cmp_lt_i32_e32 vcc, v31, v29
	v_mov_b32_e32 v36, v11
	v_mov_b32_e32 v37, v3
	v_mov_b32_e32 v24, v10
	v_mov_b32_e32 v25, v2
	v_pk_mul_f32 v[36:37], v[36:37], v[36:37]
	s_nop 0
	v_pk_fma_f32 v[24:25], v[24:25], v[24:25], v[36:37]
	v_mov_b32_e32 v36, v12
	v_mov_b32_e32 v37, v4
	v_pk_fma_f32 v[24:25], v[36:37], v[36:37], v[24:25]
	v_mov_b32_e32 v36, v13
	v_mov_b32_e32 v37, v5
	v_pk_fma_f32 v[24:25], v[36:37], v[36:37], v[24:25]
	s_nop 0
	v_add_f32_e32 v22, v22, v24
	v_add_f32_e32 v22, v22, v25
	ds_bpermute_b32 v23, v23, v22
	s_waitcnt lgkmcnt(0)
	v_add_f32_e32 v22, v22, v23
	v_cndmask_b32_e32 v23, v28, v31, vcc
	v_lshlrev_b32_e32 v23, 2, v23
	ds_bpermute_b32 v23, v23, v22
	v_cmp_lt_i32_e32 vcc, v32, v29
	s_waitcnt lgkmcnt(0)
	v_add_f32_e32 v22, v22, v23
	v_cndmask_b32_e32 v23, v28, v32, vcc
	v_lshlrev_b32_e32 v23, 2, v23
	ds_bpermute_b32 v23, v23, v22
	v_cmp_lt_i32_e32 vcc, v33, v29
	s_waitcnt lgkmcnt(0)
	v_add_f32_e32 v22, v22, v23
	v_cndmask_b32_e32 v23, v28, v33, vcc
	v_lshlrev_b32_e32 v23, 2, v23
	ds_bpermute_b32 v23, v23, v22
	v_cmp_lt_i32_e32 vcc, v34, v29
	s_waitcnt lgkmcnt(0)
	v_add_f32_e32 v22, v22, v23
	v_cndmask_b32_e32 v23, v28, v34, vcc
	v_lshlrev_b32_e32 v23, 2, v23
	ds_bpermute_b32 v23, v23, v22
	v_cmp_lt_i32_e32 vcc, v35, v29
	s_waitcnt lgkmcnt(0)
	v_add_f32_e32 v22, v22, v23
	v_cndmask_b32_e32 v23, v28, v35, vcc
	v_lshlrev_b32_e32 v23, 2, v23
	ds_bpermute_b32 v23, v23, v22
	s_waitcnt lgkmcnt(0)
	v_add_f32_e32 v22, v22, v23
	v_fmamk_f32 v22, v22, 0x3a800000, v27
	v_cmp_gt_f32_e32 vcc, s2, v22
	v_mul_f32_e32 v23, 0x4b800000, v22
	s_nop 0
	v_cndmask_b32_e32 v22, v22, v23, vcc
	v_rsq_f32_e32 v22, v22
	s_nop 0
	v_mul_f32_e32 v23, 0x45800000, v22
	v_cndmask_b32_e32 v22, v22, v23, vcc
	v_pk_mul_f32 v[14:15], v[14:15], v[22:23] op_sel_hi:[1,0]
	v_pk_mul_f32 v[16:17], v[16:17], v[22:23] op_sel_hi:[1,0]
	v_pk_mul_f32 v[6:7], v[6:7], v[22:23] op_sel_hi:[1,0]
	v_pk_mul_f32 v[8:9], v[8:9], v[22:23] op_sel_hi:[1,0]
	v_pk_mul_f32 v[10:11], v[10:11], v[22:23] op_sel_hi:[1,0]
	v_pk_mul_f32 v[12:13], v[12:13], v[22:23] op_sel_hi:[1,0]
	v_pk_mul_f32 v[2:3], v[2:3], v[22:23] op_sel_hi:[1,0]
	v_pk_mul_f32 v[4:5], v[4:5], v[22:23] op_sel_hi:[1,0]
	s_waitcnt vmcnt(0)
	v_pk_mul_f32 v[14:15], v[228:229], v[14:15]
	v_pk_mul_f32 v[16:17], v[230:231], v[16:17]
	v_pk_mul_f32 v[6:7], v[232:233], v[6:7]
	v_pk_mul_f32 v[8:9], v[234:235], v[8:9]
	v_pk_mul_f32 v[10:11], v[236:237], v[10:11]
	v_pk_mul_f32 v[12:13], v[238:239], v[12:13]
	v_pk_mul_f32 v[2:3], v[240:241], v[2:3]
	v_pk_mul_f32 v[4:5], v[242:243], v[4:5]
	v_cvt_pk_bf16_f32 v14, v14, v15
	v_cvt_pk_bf16_f32 v15, v16, v17
	v_cvt_pk_bf16_f32 v6, v6, v7
	v_cvt_pk_bf16_f32 v7, v8, v9
	v_cvt_pk_bf16_f32 v10, v10, v11
	v_cvt_pk_bf16_f32 v11, v12, v13
	v_cvt_pk_bf16_f32 v2, v2, v3
	v_cvt_pk_bf16_f32 v3, v4, v5
	global_store_dwordx2 v[20:21], v[14:15], off
	global_store_dwordx2 v[20:21], v[6:7], off offset:512
	global_store_dwordx2 v[20:21], v[10:11], off offset:1024
	global_store_dwordx2 v[20:21], v[2:3], off offset:1536

; __device__ __forceinline__ void gemm_mainloop_256(const u16* __restrict__ A, const u16* __restrict__ Bt,
;                                                   f32x16 (&acc)[4][2], char* smem) {
;     ...
;   for (int kt = 0; kt < 16; ++kt) {
;     __syncthreads();
; #pragma unroll
;     for (int i = 0; i < 8; ++i) *(u32x4*)(As + wofs + i * 32 * 72) = ra[i];
; #pragma unroll
;     for (int i = 0; i < 4; ++i) *(u32x4*)(Bs + wofs + i * 32 * 72) = rb4[i];
;     __syncthreads();
;     if (kt + 1 < 16) gl(kt + 1);
;     __builtin_amdgcn_sched_barrier(0);
; #pragma unroll
;     for (int ks = 0; ks < 4; ++ks) {
;       bf16x8 af[4], bfr[2];
; #pragma unroll
;       for (int i = 0; i < 4; ++i) af[i] = *(const bf16x8*)(As + aofs + i * 32 * 72 + ks * 16);
; #pragma unroll
;       for (int j = 0; j < 2; ++j) bfr[j] = *(const bf16x8*)(Bs + bofs + j * 32 * 72 + ks * 16);
; #pragma unroll
;       for (int i = 0; i < 4; ++i)
; #pragma unroll
;         for (int j = 0; j < 2; ++j)
;           acc[i][j] = __builtin_amdgcn_mfma_f32_32x32x16_bf16(af[i], bfr[j], acc[i][j], 0, 0, 0);
;     }
;     __builtin_amdgcn_sched_barrier(0);
;   }
.LBB0_118:
	s_waitcnt lgkmcnt(0)
	s_barrier
	s_mov_b32 s2, 0x70000
	v_lshl_add_u64 v[188:189], v[184:185], 0, s[0:1]
	v_lshl_add_u64 v[190:191], v[186:187], 0, s[0:1]
	s_waitcnt vmcnt(0)
	ds_write_b128 v133, v[134:137]
	ds_write_b128 v133, v[142:145] offset:4608
	v_add_co_u32_e32 v192, vcc, s37, v188
	ds_write_b128 v133, v[146:149] offset:9216
	s_nop 0
	v_addc_co_u32_e32 v193, vcc, 0, v189, vcc
	v_add_co_u32_e32 v194, vcc, s17, v188
	ds_write_b128 v133, v[150:153] offset:13824
	s_nop 0
	v_addc_co_u32_e32 v195, vcc, 0, v189, vcc
	v_add_co_u32_e32 v202, vcc, s19, v188
	ds_write_b128 v133, v[154:157] offset:18432
	s_nop 0
	v_addc_co_u32_e32 v203, vcc, 0, v189, vcc
	v_add_co_u32_e32 v204, vcc, s23, v188
	ds_write_b128 v133, v[158:161] offset:23040
	s_nop 0
	v_addc_co_u32_e32 v205, vcc, 0, v189, vcc
	v_add_co_u32_e32 v206, vcc, s3, v188
	ds_write_b128 v133, v[162:165] offset:27648
	s_nop 0
	v_addc_co_u32_e32 v207, vcc, 0, v189, vcc
	v_add_co_u32_e32 v208, vcc, s15, v188
	ds_write_b128 v133, v[166:169] offset:32256
	s_nop 0
	v_addc_co_u32_e32 v209, vcc, 0, v189, vcc
	v_add_co_u32_e32 v210, vcc, s2, v188
	ds_write_b128 v133, v[138:141] offset:36864
	s_nop 0
	v_addc_co_u32_e32 v211, vcc, 0, v189, vcc
	v_add_co_u32_e32 v212, vcc, s37, v190
	ds_write_b128 v133, v[170:173] offset:41472
	s_nop 0
	v_addc_co_u32_e32 v213, vcc, 0, v191, vcc
	v_add_co_u32_e32 v214, vcc, s17, v190
	ds_write_b128 v133, v[174:177] offset:46080
	s_nop 0
	v_addc_co_u32_e32 v215, vcc, 0, v191, vcc
	v_add_co_u32_e32 v216, vcc, s19, v190
	ds_write_b128 v133, v[178:181] offset:50688
	s_nop 0
	v_addc_co_u32_e32 v217, vcc, 0, v191, vcc
	s_waitcnt lgkmcnt(0)
	s_barrier
	global_load_dwordx4 v[134:137], v[188:189], off offset:128
	global_load_dwordx4 v[138:141], v[190:191], off offset:128
	global_load_dwordx4 v[142:145], v[192:193], off offset:128
	global_load_dwordx4 v[146:149], v[194:195], off offset:128
	global_load_dwordx4 v[150:153], v[202:203], off offset:128
	global_load_dwordx4 v[154:157], v[204:205], off offset:128
	global_load_dwordx4 v[158:161], v[206:207], off offset:128
	global_load_dwordx4 v[162:165], v[208:209], off offset:128
	global_load_dwordx4 v[166:169], v[210:211], off offset:128
	global_load_dwordx4 v[170:173], v[212:213], off offset:128
	global_load_dwordx4 v[174:177], v[214:215], off offset:128
	global_load_dwordx4 v[178:181], v[216:217], off offset:128
	ds_read_b128 v[188:191], v182
	ds_read_b128 v[192:195], v130 offset:36864
	ds_read_b128 v[202:205], v130 offset:41472
	ds_read_b128 v[206:209], v182 offset:4608
	ds_read_b128 v[210:213], v182 offset:9216
	ds_read_b128 v[214:217], v182 offset:13824
	s_waitcnt lgkmcnt(4)
	v_mfma_f32_32x32x16_bf16 v[114:129], v[188:191], v[192:195], v[114:129]
	s_waitcnt lgkmcnt(3)
	v_mfma_f32_32x32x16_bf16 v[98:113], v[188:191], v[202:205], v[98:113]
	ds_read_b128 v[188:191], v182 offset:32
	ds_read_b128 v[218:221], v130 offset:36896
	ds_read_b128 v[222:225], v130 offset:41504
	s_waitcnt lgkmcnt(5)
	v_mfma_f32_32x32x16_bf16 v[82:97], v[206:209], v[192:195], v[82:97]
	v_mfma_f32_32x32x16_bf16 v[66:81], v[206:209], v[202:205], v[66:81]
	ds_read_b128 v[206:209], v182 offset:4640
	s_waitcnt lgkmcnt(5)
	v_mfma_f32_32x32x16_bf16 v[50:65], v[210:213], v[192:195], v[50:65]
	v_mfma_f32_32x32x16_bf16 v[34:49], v[210:213], v[202:205], v[34:49]
	ds_read_b128 v[210:213], v182 offset:9248
	s_waitcnt lgkmcnt(5)
	v_mfma_f32_32x32x16_bf16 v[18:33], v[214:217], v[192:195], v[18:33]
	v_mfma_f32_32x32x16_bf16 v[2:17], v[214:217], v[202:205], v[2:17]
	ds_read_b128 v[214:217], v182 offset:13856
	s_waitcnt lgkmcnt(4)
	v_mfma_f32_32x32x16_bf16 v[114:129], v[188:191], v[218:221], v[114:129]
	s_waitcnt lgkmcnt(3)
	v_mfma_f32_32x32x16_bf16 v[98:113], v[188:191], v[222:225], v[98:113]
	ds_read_b128 v[188:191], v182 offset:64
	ds_read_b128 v[192:195], v130 offset:36928
	ds_read_b128 v[202:205], v130 offset:41536
	s_waitcnt lgkmcnt(5)
	v_mfma_f32_32x32x16_bf16 v[82:97], v[206:209], v[218:221], v[82:97]
	v_mfma_f32_32x32x16_bf16 v[66:81], v[206:209], v[222:225], v[66:81]
	ds_read_b128 v[206:209], v182 offset:4672
	s_waitcnt lgkmcnt(5)
	v_mfma_f32_32x32x16_bf16 v[50:65], v[210:213], v[218:221], v[50:65]
	v_mfma_f32_32x32x16_bf16 v[34:49], v[210:213], v[222:225], v[34:49]
	ds_read_b128 v[210:213], v182 offset:9280
	s_waitcnt lgkmcnt(5)
	v_mfma_f32_32x32x16_bf16 v[18:33], v[214:217], v[218:221], v[18:33]
	v_mfma_f32_32x32x16_bf16 v[2:17], v[214:217], v[222:225], v[2:17]
	ds_read_b128 v[214:217], v182 offset:13888
	s_waitcnt lgkmcnt(4)
	v_mfma_f32_32x32x16_bf16 v[114:129], v[188:191], v[192:195], v[114:129]
	s_waitcnt lgkmcnt(3)
	v_mfma_f32_32x32x16_bf16 v[98:113], v[188:191], v[202:205], v[98:113]
	ds_read_b128 v[188:191], v182 offset:96
	ds_read_b128 v[218:221], v130 offset:36960
	ds_read_b128 v[222:225], v130 offset:41568
	s_waitcnt lgkmcnt(5)
	v_mfma_f32_32x32x16_bf16 v[82:97], v[206:209], v[192:195], v[82:97]
	v_mfma_f32_32x32x16_bf16 v[66:81], v[206:209], v[202:205], v[66:81]
	ds_read_b128 v[206:209], v182 offset:4704
	s_waitcnt lgkmcnt(5)
	v_mfma_f32_32x32x16_bf16 v[50:65], v[210:213], v[192:195], v[50:65]
	v_mfma_f32_32x32x16_bf16 v[34:49], v[210:213], v[202:205], v[34:49]
	ds_read_b128 v[210:213], v182 offset:9312
	s_waitcnt lgkmcnt(5)
	v_mfma_f32_32x32x16_bf16 v[18:33], v[214:217], v[192:195], v[18:33]
	v_mfma_f32_32x32x16_bf16 v[2:17], v[214:217], v[202:205], v[2:17]
	ds_read_b128 v[214:217], v182 offset:13920
	s_waitcnt lgkmcnt(4)
	v_mfma_f32_32x32x16_bf16 v[114:129], v[188:191], v[218:221], v[114:129]
	s_waitcnt lgkmcnt(3)
	v_mfma_f32_32x32x16_bf16 v[98:113], v[188:191], v[222:225], v[98:113]
	s_waitcnt lgkmcnt(2)
	v_mfma_f32_32x32x16_bf16 v[82:97], v[206:209], v[218:221], v[82:97]
	v_mfma_f32_32x32x16_bf16 v[66:81], v[206:209], v[222:225], v[66:81]
	s_waitcnt lgkmcnt(1)
	v_mfma_f32_32x32x16_bf16 v[50:65], v[210:213], v[218:221], v[50:65]
	v_mfma_f32_32x32x16_bf16 v[34:49], v[210:213], v[222:225], v[34:49]
	s_waitcnt lgkmcnt(0)
	v_mfma_f32_32x32x16_bf16 v[18:33], v[214:217], v[218:221], v[18:33]
	v_mfma_f32_32x32x16_bf16 v[2:17], v[214:217], v[222:225], v[2:17]
	s_add_u32 s0, s0, 0x80
	s_addc_u32 s1, s1, 0
	s_cmpk_lg_i32 s0, 0x780
	s_cbranch_scc1 .LBB0_118
; __device__ __forceinline__ void gemm_mainloop_256(const u16* __restrict__ A, const u16* __restrict__ Bt,
;                                                   f32x16 (&acc)[4][2], char* smem) {
;     ...
;   for (int kt = 0; kt < 16; ++kt) {
;     __syncthreads();
; #pragma unroll
;     for (int i = 0; i < 8; ++i) *(u32x4*)(As + wofs + i * 32 * 72) = ra[i];
; #pragma unroll
;     for (int i = 0; i < 4; ++i) *(u32x4*)(Bs + wofs + i * 32 * 72) = rb4[i];
;     __syncthreads();
;     if (kt + 1 < 16) gl(kt + 1);
;     __builtin_amdgcn_sched_barrier(0);
; #pragma unroll
;     for (int ks = 0; ks < 4; ++ks) {
;       bf16x8 af[4], bfr[2];
; #pragma unroll
;       for (int i = 0; i < 4; ++i) af[i] = *(const bf16x8*)(As + aofs + i * 32 * 72 + ks * 16);
; #pragma unroll
;       for (int j = 0; j < 2; ++j) bfr[j] = *(const bf16x8*)(Bs + bofs + j * 32 * 72 + ks * 16);
; #pragma unroll
;       for (int i = 0; i < 4; ++i)
; #pragma unroll
;         for (int j = 0; j < 2; ++j)
;           acc[i][j] = __builtin_amdgcn_mfma_f32_32x32x16_bf16(af[i], bfr[j], acc[i][j], 0, 0, 0);
;     }
;     __builtin_amdgcn_sched_barrier(0);
;   }
;   __syncthreads();
	s_barrier
	s_waitcnt vmcnt(10)
	ds_write_b128 v133, v[134:137]
	s_waitcnt vmcnt(9)
	ds_write_b128 v133, v[142:145] offset:4608
	s_waitcnt vmcnt(8)
	ds_write_b128 v133, v[146:149] offset:9216
	s_waitcnt vmcnt(7)
	ds_write_b128 v133, v[150:153] offset:13824
	s_waitcnt vmcnt(6)
	ds_write_b128 v133, v[154:157] offset:18432
	s_waitcnt vmcnt(5)
	ds_write_b128 v133, v[158:161] offset:23040
	s_waitcnt vmcnt(4)
	ds_write_b128 v133, v[162:165] offset:27648
	s_waitcnt vmcnt(3)
	ds_write_b128 v133, v[166:169] offset:32256
	ds_write_b128 v133, v[138:141] offset:36864
	s_waitcnt vmcnt(2)
	ds_write_b128 v133, v[170:173] offset:41472
	s_waitcnt vmcnt(1)
	ds_write_b128 v133, v[174:177] offset:46080
	s_waitcnt vmcnt(0)
	ds_write_b128 v133, v[178:181] offset:50688
	s_waitcnt lgkmcnt(0)
	s_barrier
	ds_read_b128 v[134:137], v182
	ds_read_b128 v[138:141], v130 offset:36864
	ds_read_b128 v[142:145], v130 offset:41472
	ds_read_b128 v[206:209], v182 offset:4608
	ds_read_b128 v[210:213], v182 offset:9216
	ds_read_b128 v[214:217], v182 offset:13824
	s_waitcnt lgkmcnt(4)
	v_mfma_f32_32x32x16_bf16 v[114:129], v[134:137], v[138:141], v[114:129]
	s_waitcnt lgkmcnt(3)
	v_mfma_f32_32x32x16_bf16 v[98:113], v[134:137], v[142:145], v[98:113]
	ds_read_b128 v[134:137], v182 offset:32
	ds_read_b128 v[218:221], v130 offset:36896
	ds_read_b128 v[222:225], v130 offset:41504
	s_waitcnt lgkmcnt(5)
	v_mfma_f32_32x32x16_bf16 v[82:97], v[206:209], v[138:141], v[82:97]
	v_mfma_f32_32x32x16_bf16 v[66:81], v[206:209], v[142:145], v[66:81]
	ds_read_b128 v[206:209], v182 offset:4640
	s_waitcnt lgkmcnt(5)
	v_mfma_f32_32x32x16_bf16 v[50:65], v[210:213], v[138:141], v[50:65]
	v_mfma_f32_32x32x16_bf16 v[34:49], v[210:213], v[142:145], v[34:49]
	ds_read_b128 v[210:213], v182 offset:9248
	s_waitcnt lgkmcnt(5)
	v_mfma_f32_32x32x16_bf16 v[18:33], v[214:217], v[138:141], v[18:33]
	v_mfma_f32_32x32x16_bf16 v[2:17], v[214:217], v[142:145], v[2:17]
	ds_read_b128 v[214:217], v182 offset:13856
	s_waitcnt lgkmcnt(4)
	v_mfma_f32_32x32x16_bf16 v[114:129], v[134:137], v[218:221], v[114:129]
	s_waitcnt lgkmcnt(3)
	v_mfma_f32_32x32x16_bf16 v[98:113], v[134:137], v[222:225], v[98:113]
	ds_read_b128 v[134:137], v182 offset:64
	ds_read_b128 v[138:141], v130 offset:36928
	ds_read_b128 v[142:145], v130 offset:41536
	s_waitcnt lgkmcnt(5)
	v_mfma_f32_32x32x16_bf16 v[82:97], v[206:209], v[218:221], v[82:97]
	v_mfma_f32_32x32x16_bf16 v[66:81], v[206:209], v[222:225], v[66:81]
	ds_read_b128 v[206:209], v182 offset:4672
	s_waitcnt lgkmcnt(5)
	v_mfma_f32_32x32x16_bf16 v[50:65], v[210:213], v[218:221], v[50:65]
	v_mfma_f32_32x32x16_bf16 v[34:49], v[210:213], v[222:225], v[34:49]
	ds_read_b128 v[210:213], v182 offset:9280
	s_waitcnt lgkmcnt(5)
	v_mfma_f32_32x32x16_bf16 v[18:33], v[214:217], v[218:221], v[18:33]
	v_mfma_f32_32x32x16_bf16 v[2:17], v[214:217], v[222:225], v[2:17]
	ds_read_b128 v[214:217], v182 offset:13888
	s_waitcnt lgkmcnt(4)
	v_mfma_f32_32x32x16_bf16 v[114:129], v[134:137], v[138:141], v[114:129]
	s_waitcnt lgkmcnt(3)
	v_mfma_f32_32x32x16_bf16 v[98:113], v[134:137], v[142:145], v[98:113]
	ds_read_b128 v[134:137], v182 offset:96
	ds_read_b128 v[218:221], v130 offset:36960
	ds_read_b128 v[222:225], v130 offset:41568
	s_waitcnt lgkmcnt(5)
	v_mfma_f32_32x32x16_bf16 v[82:97], v[206:209], v[138:141], v[82:97]
	v_mfma_f32_32x32x16_bf16 v[66:81], v[206:209], v[142:145], v[66:81]
	ds_read_b128 v[206:209], v182 offset:4704
	s_waitcnt lgkmcnt(5)
	v_mfma_f32_32x32x16_bf16 v[50:65], v[210:213], v[138:141], v[50:65]
	v_mfma_f32_32x32x16_bf16 v[34:49], v[210:213], v[142:145], v[34:49]
	ds_read_b128 v[210:213], v182 offset:9312
	s_waitcnt lgkmcnt(5)
	v_mfma_f32_32x32x16_bf16 v[18:33], v[214:217], v[138:141], v[18:33]
	v_mfma_f32_32x32x16_bf16 v[2:17], v[214:217], v[142:145], v[2:17]
	ds_read_b128 v[214:217], v182 offset:13920
	s_waitcnt lgkmcnt(4)
	v_mfma_f32_32x32x16_bf16 v[114:129], v[134:137], v[218:221], v[114:129]
	s_waitcnt lgkmcnt(3)
	v_mfma_f32_32x32x16_bf16 v[98:113], v[134:137], v[222:225], v[98:113]
	s_waitcnt lgkmcnt(2)
	v_mfma_f32_32x32x16_bf16 v[82:97], v[206:209], v[218:221], v[82:97]
	v_mfma_f32_32x32x16_bf16 v[66:81], v[206:209], v[222:225], v[66:81]
	s_waitcnt lgkmcnt(1)
	v_mfma_f32_32x32x16_bf16 v[50:65], v[210:213], v[218:221], v[50:65]
	v_mfma_f32_32x32x16_bf16 v[34:49], v[210:213], v[222:225], v[34:49]
	s_waitcnt lgkmcnt(0)
	v_mfma_f32_32x32x16_bf16 v[18:33], v[214:217], v[218:221], v[18:33]
	v_mfma_f32_32x32x16_bf16 v[2:17], v[214:217], v[222:225], v[2:17]
	v_mov_b32_e32 v130, v198
	s_barrier
; template <int Q>
; __device__ __forceinline__ void stage_c4(const f32x16 (&acc)[4][2], float* Cs) {
;   const int tid = tid_opaque(), lane = tid & 63, w = tid >> 6, wm = w >> 1, wn = w & 1;
;   if (wm == (Q >> 1)) {
; #pragma unroll
;     for (int ii = 0; ii < 2; ++ii)
; #pragma unroll
;       for (int j = 0; j < 2; ++j)
; #pragma unroll
;         for (int r = 0; r < 16; ++r) {
;           int row = ii * 32 + (r & 3) + 8 * (r >> 2) + 4 * (lane >> 5);
;           int col = wn * 64 + j * 32 + (lane & 31);
;           Cs[row * 132 + col] = acc[2 * (Q & 1) + ii][j][r];
;         }
;   }
; }
	s_nop 0
	v_cmp_gt_u32_e32 vcc, s14, v130
	s_and_saveexec_b64 s[0:1], vcc
	s_cbranch_execz .LBB0_121
	v_lshrrev_b32_e32 v133, 3, v130
	v_lshlrev_b32_e32 v130, 2, v130
	v_and_b32_e32 v134, 4, v133
	v_and_b32_e32 v135, 0x17c, v130
	v_mad_u32_u24 v136, v134, s18, v135
	v_add_u32_e32 v137, 0x400, v136
	ds_write2_b32 v137, v116, v117 offset0:8 offset1:140
	v_add_u32_e32 v137, 0x1000, v136
	ds_write2_b32 v136, v114, v115 offset1:132
	ds_write2_b32 v137, v118, v119 offset0:32 offset1:164
	ds_write_b32 v136, v120 offset:5280
	v_or_b32_e32 v137, 11, v133
	v_mul_lo_u32 v137, v137, s18
	v_add_u32_e32 v138, v137, v135
	ds_write_b32 v138, v121
	v_add_u32_e32 v138, 0x2000, v136
	ds_write2_b32 v138, v122, v123 offset0:64 offset1:196
	v_add_u32_e32 v138, 0x2400, v136
	ds_write2_b32 v138, v124, v125 offset0:72 offset1:204
	v_add_u32_e32 v138, 0x3000, v136
	ds_write2_b32 v138, v126, v127 offset0:96 offset1:228
	ds_write_b32 v136, v128 offset:13728
	v_or_b32_e32 v138, 27, v133
	v_mul_lo_u32 v138, v138, s18
	v_or_b32_e32 v130, 0x80, v130
	v_add_u32_e32 v139, v138, v135
	v_mad_u32_u24 v134, v134, s18, v130
	ds_write_b32 v139, v129
	v_add_u32_e32 v139, 0x400, v134
	ds_write2_b32 v139, v100, v101 offset0:8 offset1:140
	v_add_u32_e32 v139, 0x1000, v134
	v_add_u32_e32 v137, v137, v130
	ds_write2_b32 v134, v98, v99 offset1:132
	ds_write2_b32 v139, v102, v103 offset0:32 offset1:164
	ds_write_b32 v134, v104 offset:5280
	ds_write_b32 v137, v105
	v_add_u32_e32 v137, 0x2000, v134
	ds_write2_b32 v137, v106, v107 offset0:64 offset1:196
	v_add_u32_e32 v137, 0x2400, v134
	ds_write2_b32 v137, v108, v109 offset0:72 offset1:204
	v_add_u32_e32 v137, 0x3000, v134
	ds_write2_b32 v137, v110, v111 offset0:96 offset1:228
	ds_write_b32 v134, v112 offset:13728
	v_add_u32_e32 v137, v138, v130
	ds_write_b32 v137, v113
	v_add_u32_e32 v137, 0x4200, v136
	ds_write2_b32 v137, v82, v83 offset1:132
	v_add_u32_e32 v137, 0x4600, v136
	ds_write2_b32 v137, v84, v85 offset0:8 offset1:140
	v_add_u32_e32 v137, 0x5200, v136
	ds_write2_b32 v137, v86, v87 offset0:32 offset1:164
	ds_write_b32 v136, v88 offset:22176
	v_or_b32_e32 v137, 43, v133
	v_mul_lo_u32 v137, v137, s18
	v_add_u32_e32 v138, v137, v135
	ds_write_b32 v138, v89
	v_add_u32_e32 v138, 0x6200, v136
	v_or_b32_e32 v133, 59, v133
	ds_write2_b32 v138, v90, v91 offset0:64 offset1:196
	v_add_u32_e32 v138, 0x6600, v136
	v_mul_lo_u32 v133, v133, s18
	ds_write2_b32 v138, v92, v93 offset0:72 offset1:204
	v_add_u32_e32 v138, 0x7200, v136
	v_add_u32_e32 v135, v133, v135
	ds_write2_b32 v138, v94, v95 offset0:96 offset1:228
	ds_write_b32 v136, v96 offset:30624
	ds_write_b32 v135, v97
	v_add_u32_e32 v135, 0x4200, v134
	ds_write2_b32 v135, v66, v67 offset1:132
	v_add_u32_e32 v135, 0x4600, v134
	ds_write2_b32 v135, v68, v69 offset0:8 offset1:140
	v_add_u32_e32 v135, 0x5200, v134
	ds_write2_b32 v135, v70, v71 offset0:32 offset1:164
	ds_write_b32 v134, v72 offset:22176
	v_add_u32_e32 v135, v137, v130
	ds_write_b32 v135, v73
	v_add_u32_e32 v135, 0x6200, v134
	ds_write2_b32 v135, v74, v75 offset0:64 offset1:196
	v_add_u32_e32 v135, 0x6600, v134
	ds_write2_b32 v135, v76, v77 offset0:72 offset1:204
	v_add_u32_e32 v135, 0x7200, v134
	v_add_u32_e32 v130, v133, v130
	ds_write2_b32 v135, v78, v79 offset0:96 offset1:228
	ds_write_b32 v134, v80 offset:30624
	ds_write_b32 v130, v81

; template <bool ROWRMS>
; __device__ __forceinline__ void gemm_mainloop(const u16* __restrict__ A, int lda, const u16* __restrict__ Bt, int ldb,
;                                               int K, f32x16 (&acc)[2][2], char* smem, float* rs) {
;     ...
; #pragma unroll
;     for (int kh = 0; kh < 2; ++kh) {
;       bf16x8 af[2][2], bfr[2][2];
; #pragma unroll
;       for (int ks = 0; ks < 2; ++ks) {
; #pragma unroll
;         for (int i = 0; i < 2; ++i) af[ks][i] = *(const bf16x8*)(As + aofs + i * 32 * 72 + (kh * 2 + ks) * 16);
; #pragma unroll
;         for (int j = 0; j < 2; ++j) bfr[ks][j] = *(const bf16x8*)(Bs + bofs + j * 32 * 72 + (kh * 2 + ks) * 16);
;       }
; #pragma unroll
;       for (int ks = 0; ks < 2; ++ks)
; #pragma unroll
;         for (int i = 0; i < 2; ++i)
; #pragma unroll
;           for (int j = 0; j < 2; ++j)
;             acc[i][j] = __builtin_amdgcn_mfma_f32_32x32x16_bf16(af[ks][i], bfr[ks][j], acc[i][j], 0, 0, 0);
;     }
.LBB0_662:
	s_add_i32 s2, s2, 2
	ds_read_b128 v[188:191], v142
	ds_read_b128 v[228:231], v143 offset:18432
	ds_read_b128 v[232:235], v143 offset:23040
	ds_read_b128 v[192:195], v142 offset:4608
	ds_read_b128 v[200:203], v142 offset:32
	ds_read_b128 v[236:239], v143 offset:18464
	ds_read_b128 v[240:243], v143 offset:23072
	ds_read_b128 v[204:207], v142 offset:4640
	s_waitcnt lgkmcnt(6)
	v_mfma_f32_32x32x16_bf16 v[50:65], v[188:191], v[228:231], v[50:65]
	s_waitcnt lgkmcnt(5)
	v_mfma_f32_32x32x16_bf16 v[34:49], v[188:191], v[232:235], v[34:49]
	s_waitcnt lgkmcnt(4)
	v_mfma_f32_32x32x16_bf16 v[18:33], v[192:195], v[228:231], v[18:33]
	v_mfma_f32_32x32x16_bf16 v[2:17], v[192:195], v[232:235], v[2:17]
	ds_read_b128 v[188:191], v142 offset:64
	ds_read_b128 v[228:231], v143 offset:18496
	ds_read_b128 v[232:235], v143 offset:23104
	ds_read_b128 v[192:195], v142 offset:4672
	s_waitcnt lgkmcnt(6)
	v_mfma_f32_32x32x16_bf16 v[50:65], v[200:203], v[236:239], v[50:65]
	s_waitcnt lgkmcnt(5)
	v_mfma_f32_32x32x16_bf16 v[34:49], v[200:203], v[240:243], v[34:49]
	s_waitcnt lgkmcnt(4)
	v_mfma_f32_32x32x16_bf16 v[18:33], v[204:207], v[236:239], v[18:33]
	v_mfma_f32_32x32x16_bf16 v[2:17], v[204:207], v[240:243], v[2:17]
	ds_read_b128 v[200:203], v142 offset:96
	ds_read_b128 v[236:239], v143 offset:18528
	ds_read_b128 v[240:243], v143 offset:23136
	ds_read_b128 v[204:207], v142 offset:4704
	s_waitcnt lgkmcnt(6)
	v_mfma_f32_32x32x16_bf16 v[50:65], v[188:191], v[228:231], v[50:65]
	s_waitcnt lgkmcnt(5)
	v_mfma_f32_32x32x16_bf16 v[34:49], v[188:191], v[232:235], v[34:49]
	s_waitcnt lgkmcnt(4)
	v_mfma_f32_32x32x16_bf16 v[18:33], v[192:195], v[228:231], v[18:33]
	v_mfma_f32_32x32x16_bf16 v[2:17], v[192:195], v[232:235], v[2:17]
	s_waitcnt lgkmcnt(2)
	v_mfma_f32_32x32x16_bf16 v[50:65], v[200:203], v[236:239], v[50:65]
	s_waitcnt lgkmcnt(1)
	v_mfma_f32_32x32x16_bf16 v[34:49], v[200:203], v[240:243], v[34:49]
	s_waitcnt lgkmcnt(0)
	v_mfma_f32_32x32x16_bf16 v[18:33], v[204:207], v[236:239], v[18:33]
	v_mfma_f32_32x32x16_bf16 v[2:17], v[204:207], v[240:243], v[2:17]
	v_lshl_add_u64 v[138:139], v[138:139], 0, s[10:11]
	s_andn2_b64 vcc, exec, s[6:7]
	v_lshl_add_u64 v[140:141], v[140:141], 0, s[10:11]
	s_cbranch_vccz .LBB0_667

; template <bool ROWRMS>
; __device__ __forceinline__ void gemm_mainloop(const u16* __restrict__ A, int lda, const u16* __restrict__ Bt, int ldb,
;                                               int K, f32x16 (&acc)[2][2], char* smem, float* rs) {
;     ...
;   auto step = [&](GRegs& R, int kt) {
;     __syncthreads();
; #pragma unroll
;     for (int i = 0; i < 4; ++i) {
;       *(u32x4*)(As + wofs + i * 32 * 72) = R.a[i];
;       *(u32x4*)(Bs + wofs + i * 32 * 72) = R.b[i];
;     }
;     if (ROWRMS) {
; #pragma unroll
;       for (int i = 0; i < 4; ++i) {
;         unsigned a[4] = {R.a[i].x, R.a[i].y, R.a[i].z, R.a[i].w};
; #pragma unroll
;         for (int e = 0; e < 4; ++e) {
;           float lo = __uint_as_float(a[e] << 16), hi = __uint_as_float(a[e] & 0xffff0000u);
;           ss[i] += lo * lo + hi * hi;
;         }
;       }
;     }
;     __syncthreads();
;     if (kt + 2 < nk) gl(R, kt + 2);
;     __builtin_amdgcn_sched_barrier(0);
; #pragma unroll
;     for (int kh = 0; kh < 2; ++kh) {
;       bf16x8 af[2][2], bfr[2][2];
; #pragma unroll
;       for (int ks = 0; ks < 2; ++ks) {
; #pragma unroll
;         for (int i = 0; i < 2; ++i) af[ks][i] = *(const bf16x8*)(As + aofs + i * 32 * 72 + (kh * 2 + ks) * 16);
; #pragma unroll
;         for (int j = 0; j < 2; ++j) bfr[ks][j] = *(const bf16x8*)(Bs + bofs + j * 32 * 72 + (kh * 2 + ks) * 16);
;       }
; #pragma unroll
;       for (int ks = 0; ks < 2; ++ks)
; #pragma unroll
;         for (int i = 0; i < 2; ++i)
; #pragma unroll
;           for (int j = 0; j < 2; ++j)
;             acc[i][j] = __builtin_amdgcn_mfma_f32_32x32x16_bf16(af[ks][i], bfr[ks][j], acc[i][j], 0, 0, 0);
;     }
.LBB0_665:
	ds_read_b128 v[188:191], v142
	ds_read_b128 v[228:231], v143 offset:18432
	ds_read_b128 v[232:235], v143 offset:23040
	ds_read_b128 v[192:195], v142 offset:4608
	ds_read_b128 v[200:203], v142 offset:32
	ds_read_b128 v[236:239], v143 offset:18464
	ds_read_b128 v[240:243], v143 offset:23072
	ds_read_b128 v[204:207], v142 offset:4640
	s_waitcnt lgkmcnt(6)
	v_mfma_f32_32x32x16_bf16 v[50:65], v[188:191], v[228:231], v[50:65]
	s_waitcnt lgkmcnt(5)
	v_mfma_f32_32x32x16_bf16 v[34:49], v[188:191], v[232:235], v[34:49]
	s_waitcnt lgkmcnt(4)
	v_mfma_f32_32x32x16_bf16 v[18:33], v[192:195], v[228:231], v[18:33]
	v_mfma_f32_32x32x16_bf16 v[2:17], v[192:195], v[232:235], v[2:17]
	ds_read_b128 v[188:191], v142 offset:64
	ds_read_b128 v[228:231], v143 offset:18496
	ds_read_b128 v[232:235], v143 offset:23104
	ds_read_b128 v[192:195], v142 offset:4672
	s_waitcnt lgkmcnt(6)
	v_mfma_f32_32x32x16_bf16 v[50:65], v[200:203], v[236:239], v[50:65]
	s_waitcnt lgkmcnt(5)
	v_mfma_f32_32x32x16_bf16 v[34:49], v[200:203], v[240:243], v[34:49]
	s_waitcnt lgkmcnt(4)
	v_mfma_f32_32x32x16_bf16 v[18:33], v[204:207], v[236:239], v[18:33]
	v_mfma_f32_32x32x16_bf16 v[2:17], v[204:207], v[240:243], v[2:17]
	ds_read_b128 v[200:203], v142 offset:96
	ds_read_b128 v[236:239], v143 offset:18528
	ds_read_b128 v[240:243], v143 offset:23136
	ds_read_b128 v[204:207], v142 offset:4704
	s_waitcnt lgkmcnt(6)
	v_mfma_f32_32x32x16_bf16 v[50:65], v[188:191], v[228:231], v[50:65]
	s_waitcnt lgkmcnt(5)
	v_mfma_f32_32x32x16_bf16 v[34:49], v[188:191], v[232:235], v[34:49]
	s_waitcnt lgkmcnt(4)
	v_mfma_f32_32x32x16_bf16 v[18:33], v[192:195], v[228:231], v[18:33]
	v_mfma_f32_32x32x16_bf16 v[2:17], v[192:195], v[232:235], v[2:17]
	s_waitcnt lgkmcnt(2)
	v_mfma_f32_32x32x16_bf16 v[50:65], v[200:203], v[236:239], v[50:65]
	s_waitcnt lgkmcnt(1)
	v_mfma_f32_32x32x16_bf16 v[34:49], v[200:203], v[240:243], v[34:49]
	s_waitcnt lgkmcnt(0)
	v_mfma_f32_32x32x16_bf16 v[18:33], v[204:207], v[236:239], v[18:33]
	v_mfma_f32_32x32x16_bf16 v[2:17], v[204:207], v[240:243], v[2:17]
	s_cmp_gt_u32 s2, 12
	s_barrier
	ds_write_b128 v137, v[74:77]
	ds_write_b128 v137, v[66:69] offset:18432
	ds_write_b128 v137, v[82:85] offset:4608
	ds_write_b128 v137, v[90:93] offset:23040
	ds_write_b128 v137, v[98:101] offset:9216
	ds_write_b128 v137, v[106:109] offset:27648
	ds_write_b128 v137, v[114:117] offset:13824
	ds_write_b128 v137, v[122:125] offset:32256
	s_waitcnt lgkmcnt(0)
	s_barrier
	s_cbranch_scc1 .LBB0_662
	v_add_co_u32_e32 v82, vcc, 0x10000, v146
	global_load_dwordx4 v[74:77], v[146:147], off offset:384
	global_load_dwordx4 v[66:69], v[144:145], off offset:384
	v_addc_co_u32_e32 v83, vcc, 0, v147, vcc
	v_add_co_u32_e32 v90, vcc, 0x10000, v144
	global_load_dwordx4 v[82:85], v[82:83], off offset:384
	s_nop 0
	v_addc_co_u32_e32 v91, vcc, 0, v145, vcc
	v_add_co_u32_e32 v98, vcc, 0x20000, v146
	global_load_dwordx4 v[90:93], v[90:91], off offset:384
	s_nop 0
	v_addc_co_u32_e32 v99, vcc, 0, v147, vcc
	v_add_co_u32_e32 v106, vcc, 0x20000, v144
	global_load_dwordx4 v[98:101], v[98:99], off offset:384
	s_nop 0
	v_addc_co_u32_e32 v107, vcc, 0, v145, vcc
	v_add_co_u32_e32 v114, vcc, 0x30000, v146
	global_load_dwordx4 v[106:109], v[106:107], off offset:384
	s_nop 0
	v_addc_co_u32_e32 v115, vcc, 0, v147, vcc
	v_add_co_u32_e32 v122, vcc, 0x30000, v144
	global_load_dwordx4 v[114:117], v[114:115], off offset:384
	s_nop 0
	v_addc_co_u32_e32 v123, vcc, 0, v145, vcc
	global_load_dwordx4 v[122:125], v[122:123], off offset:384
	s_branch .LBB0_662

; template <bool ROWRMS>
; __device__ __forceinline__ void gemm_mainloop(const u16* __restrict__ A, int lda, const u16* __restrict__ Bt, int ldb,
;                                               int K, f32x16 (&acc)[2][2], char* smem, float* rs) {
;   const int tid = tid_opaque(), lane = tid & 63, w = tid >> 6, wm = w >> 1, wn = w & 1;
;   u16* As = (u16*)smem;
;   u16* Bs = As + 128 * 72;
;   const int r0 = tid >> 3, kc = (tid & 7) * 8;
;   const u16* ga = A + (long)r0 * lda + kc;
;   const u16* gb = Bt + (long)r0 * ldb + kc;
;   const long a32 = 32L * lda, b32 = 32L * ldb;
;   float ss[4] = {0.f, 0.f, 0.f, 0.f};
; #pragma unroll
;   for (int i = 0; i < 2; ++i)
; #pragma unroll
;     for (int j = 0; j < 2; ++j)
; #pragma unroll
;       for (int r = 0; r < 16; ++r) acc[i][j][r] = 0.f;
;   const int nk = K >> 6;
;   const int wofs = r0 * 72 + kc;
;   const int aofs = (wm * 64 + (lane & 31)) * 72 + (lane >> 5) * 8;
;   const int bofs = (wn * 64 + (lane & 31)) * 72 + (lane >> 5) * 8;
;   auto gl = [&](GRegs& R, int kt) {
;     const int ko = kt * 64;
; #pragma unroll
;     for (int i = 0; i < 4; ++i) {
;       R.a[i] = *(const u32x4*)(ga + i * a32 + ko);
;       R.b[i] = *(const u32x4*)(gb + i * b32 + ko);
;     }
;   };
;   auto step = [&](GRegs& R, int kt) {
;     __syncthreads();
; #pragma unroll
;     for (int i = 0; i < 4; ++i) {
;       *(u32x4*)(As + wofs + i * 32 * 72) = R.a[i];
;       *(u32x4*)(Bs + wofs + i * 32 * 72) = R.b[i];
;     }
;     if (ROWRMS) {
; #pragma unroll
;       for (int i = 0; i < 4; ++i) {
;         unsigned a[4] = {R.a[i].x, R.a[i].y, R.a[i].z, R.a[i].w};
; #pragma unroll
;         for (int e = 0; e < 4; ++e) {
;           float lo = __uint_as_float(a[e] << 16), hi = __uint_as_float(a[e] & 0xffff0000u);
;           ss[i] += lo * lo + hi * hi;
;         }
;       }
;     }
;     __syncthreads();
;     if (kt + 2 < nk) gl(R, kt + 2);
;     __builtin_amdgcn_sched_barrier(0);
; #pragma unroll
;     for (int kh = 0; kh < 2; ++kh) {
;       bf16x8 af[2][2], bfr[2][2];
; #pragma unroll
;       for (int ks = 0; ks < 2; ++ks) {
; #pragma unroll
; __device__ __forceinline__ void phaseB(const P& p, int l, char* smem, unsigned* ctr) {
;     ...
;       int t = e - NKV;
;       int mt = t / 3, nt = t % 3;
;       gemm_mainloop<true>(p.bcq + (long)mt * 128 * 256, 256, p.wt_q + ((long)l * 384 + nt * 128) * 256, 256, 256, acc, smem, rs);
.LBB0_734:
	s_add_i32 s6, s38, 0xf7c0
	s_mov_b64 s[8:9], s[28:29]
	s_and_b32 s0, s6, 0xffff
	s_load_dwordx8 s[24:31], s[8:9], 0x180
	s_mul_i32 s7, s0, 0xaaab
	s_lshr_b32 s22, s7, 17
	s_mul_i32 s7, s22, 3
	s_sub_i32 s23, s6, s7
	s_lshl_b32 s6, s22, 16
	s_waitcnt lgkmcnt(0)
	s_add_u32 s6, s30, s6
	v_mov_b32_e32 v6, v198
	s_addc_u32 s7, s31, 0
	s_lshl_b32 s8, s23, 16
	s_add_u32 s8, s54, s8
	v_ashrrev_i32_e32 v156, 3, v6
	v_ashrrev_i32_e32 v157, 31, v156
	s_addc_u32 s9, s55, 0
	v_and_b32_e32 v164, 7, v6
	v_lshlrev_b64 v[2:3], 9, v[156:157]
	v_lshl_add_u64 v[4:5], s[8:9], 0, v[2:3]
	v_lshl_add_u64 v[2:3], s[6:7], 0, v[2:3]
	v_lshlrev_b32_e32 v154, 4, v164
	v_lshl_add_u64 v[142:143], v[2:3], 0, v[154:155]
	v_add_co_u32_e32 v146, vcc, s17, v142
	v_lshl_add_u64 v[144:145], v[4:5], 0, v[154:155]
	s_nop 0
	v_addc_co_u32_e32 v147, vcc, 0, v143, vcc
	v_add_co_u32_e32 v148, vcc, s17, v144
	v_lshrrev_b32_e32 v24, 1, v6
	v_and_b32_e32 v2, 31, v6
	v_addc_co_u32_e32 v149, vcc, 0, v145, vcc
	v_and_or_b32 v25, v24, s15, v2
	v_and_b32_e32 v26, 0x5f, v6
	global_load_dwordx4 v[2:5], v[142:143], off
	global_load_dwordx4 v[6:9], v[144:145], off
	v_add_co_u32_e32 v150, vcc, s21, v142
	global_load_dwordx4 v[86:89], v[146:147], off
	s_nop 0
	v_addc_co_u32_e32 v151, vcc, 0, v143, vcc
	v_add_co_u32_e32 v152, vcc, s21, v144
	global_load_dwordx4 v[10:13], v[148:149], off
	s_nop 0
	v_addc_co_u32_e32 v153, vcc, 0, v145, vcc
	global_load_dwordx4 v[78:81], v[150:151], off
	v_add_co_u32_e32 v160, vcc, s33, v142
	global_load_dwordx4 v[14:17], v[152:153], off
	s_nop 0
	v_addc_co_u32_e32 v161, vcc, 0, v143, vcc
	global_load_dwordx4 v[70:73], v[160:161], off
	v_add_co_u32_e32 v162, vcc, s33, v144
	v_lshlrev_b32_e32 v22, 3, v164
	s_nop 0
	v_addc_co_u32_e32 v163, vcc, 0, v145, vcc
	global_load_dwordx4 v[18:21], v[162:163], off
	global_load_dwordx4 v[102:105], v[142:143], off offset:128
	global_load_dwordx4 v[106:109], v[144:145], off offset:128
	global_load_dwordx4 v[90:93], v[146:147], off offset:128
	global_load_dwordx4 v[114:117], v[148:149], off offset:128
	global_load_dwordx4 v[74:77], v[150:151], off offset:128
	global_load_dwordx4 v[134:137], v[152:153], off offset:128
	global_load_dwordx4 v[66:69], v[160:161], off offset:128
	global_load_dwordx4 v[138:141], v[162:163], off offset:128
	v_mul_lo_u32 v23, v156, s13
	v_add_lshl_u32 v157, v23, v22, 1
	s_waitcnt vmcnt(63) expcnt(7) lgkmcnt(15)
	s_barrier
	v_and_b32_e32 v22, 16, v24
	v_mad_u64_u32 v[158:159], s[6:7], v25, s84, v[22:23]
	v_mad_u32_u24 v154, v26, s84, v22
	s_waitcnt vmcnt(0)
	ds_write_b128 v157, v[2:5]
	ds_write_b128 v157, v[6:9] offset:18432
	ds_write_b128 v157, v[86:89] offset:4608
	ds_write_b128 v157, v[10:13] offset:23040
	ds_write_b128 v157, v[78:81] offset:9216
	ds_write_b128 v157, v[14:17] offset:27648
	ds_write_b128 v157, v[70:73] offset:13824
	ds_write_b128 v157, v[18:21] offset:32256
	s_waitcnt lgkmcnt(0)
	s_barrier
	global_load_dwordx4 v[110:113], v[142:143], off offset:256
	global_load_dwordx4 v[118:121], v[144:145], off offset:256
	global_load_dwordx4 v[98:101], v[146:147], off offset:256
	global_load_dwordx4 v[122:125], v[148:149], off offset:256
	global_load_dwordx4 v[94:97], v[150:151], off offset:256
	global_load_dwordx4 v[126:129], v[152:153], off offset:256
	global_load_dwordx4 v[82:85], v[160:161], off offset:256
	global_load_dwordx4 v[130:133], v[162:163], off offset:256
	v_lshlrev_b32_e32 v6, 16, v2
	v_and_b32_e32 v2, 0xffff0000, v2
	v_mul_f32_e32 v2, v2, v2
	v_fmac_f32_e32 v2, v6, v6
	v_lshlrev_b32_e32 v6, 16, v3
	v_and_b32_e32 v3, 0xffff0000, v3
	v_mul_f32_e32 v3, v3, v3
	v_fmac_f32_e32 v3, v6, v6
	v_add_f32_e32 v2, v3, v2
	v_lshlrev_b32_e32 v3, 16, v4
	v_and_b32_e32 v4, 0xffff0000, v4
	v_mul_f32_e32 v4, v4, v4
	v_fmac_f32_e32 v4, v3, v3
	v_add_f32_e32 v2, v4, v2
	v_and_b32_e32 v4, 0xffff0000, v5
	v_lshlrev_b32_e32 v3, 16, v5
	v_mul_f32_e32 v4, v4, v4
	v_fmac_f32_e32 v4, v3, v3
	v_add_f32_e32 v159, v4, v2
	ds_read_b128 v[2:5], v158
	ds_read_b128 v[6:9], v154 offset:18432
	ds_read_b128 v[18:21], v154 offset:23040
	ds_read_b128 v[22:25], v158 offset:4608
	ds_read_b128 v[166:169], v158 offset:32
	ds_read_b128 v[170:173], v154 offset:18464
	ds_read_b128 v[174:177], v154 offset:23072
	s_waitcnt lgkmcnt(5)
	v_mfma_f32_32x32x16_bf16 v[34:49], v[2:5], v[6:9], 0
	s_waitcnt lgkmcnt(4)
	v_mfma_f32_32x32x16_bf16 v[50:65], v[2:5], v[18:21], 0
	s_waitcnt lgkmcnt(1)
	v_mfma_f32_32x32x16_bf16 v[34:49], v[166:169], v[170:173], v[34:49]
	s_waitcnt lgkmcnt(0)
	v_mfma_f32_32x32x16_bf16 v[50:65], v[166:169], v[174:177], v[50:65]
	ds_read_b128 v[166:169], v158 offset:4640
	v_mfma_f32_32x32x16_bf16 v[2:17], v[22:25], v[6:9], 0
	v_mfma_f32_32x32x16_bf16 v[18:33], v[22:25], v[18:21], 0
	s_waitcnt lgkmcnt(0)
	v_mfma_f32_32x32x16_bf16 v[2:17], v[166:169], v[170:173], v[2:17]
	v_mfma_f32_32x32x16_bf16 v[18:33], v[166:169], v[174:177], v[18:33]
	ds_read_b128 v[166:169], v158 offset:64
	ds_read_b128 v[170:173], v154 offset:18496
	ds_read_b128 v[174:177], v154 offset:23104
	s_waitcnt lgkmcnt(1)
	v_mfma_f32_32x32x16_bf16 v[34:49], v[166:169], v[170:173], v[34:49]
	s_waitcnt lgkmcnt(0)
	v_mfma_f32_32x32x16_bf16 v[50:65], v[166:169], v[174:177], v[50:65]
	ds_read_b128 v[166:169], v158 offset:4672
	s_waitcnt lgkmcnt(0)
	v_mfma_f32_32x32x16_bf16 v[2:17], v[166:169], v[170:173], v[2:17]
	v_mfma_f32_32x32x16_bf16 v[18:33], v[166:169], v[174:177], v[18:33]
	ds_read_b128 v[166:169], v158 offset:96
	ds_read_b128 v[170:173], v154 offset:18528
	ds_read_b128 v[174:177], v154 offset:23136
	s_waitcnt lgkmcnt(1)
	v_mfma_f32_32x32x16_bf16 v[34:49], v[166:169], v[170:173], v[34:49]
	s_waitcnt lgkmcnt(0)
	v_mfma_f32_32x32x16_bf16 v[50:65], v[166:169], v[174:177], v[50:65]
	ds_read_b128 v[166:169], v158 offset:4704
	s_waitcnt lgkmcnt(0)
	v_mfma_f32_32x32x16_bf16 v[2:17], v[166:169], v[170:173], v[2:17]
	v_mfma_f32_32x32x16_bf16 v[18:33], v[166:169], v[174:177], v[18:33]
	s_barrier
; template <bool ROWRMS>
; __device__ __forceinline__ void gemm_mainloop(const u16* __restrict__ A, int lda, const u16* __restrict__ Bt, int ldb,
;                                               int K, f32x16 (&acc)[2][2], char* smem, float* rs) {
;     ...
;   auto step = [&](GRegs& R, int kt) {
;     __syncthreads();
; #pragma unroll
;     for (int i = 0; i < 4; ++i) {
;       *(u32x4*)(As + wofs + i * 32 * 72) = R.a[i];
;       *(u32x4*)(Bs + wofs + i * 32 * 72) = R.b[i];
;     }
;     if (ROWRMS) {
; #pragma unroll
;       for (int i = 0; i < 4; ++i) {
;         unsigned a[4] = {R.a[i].x, R.a[i].y, R.a[i].z, R.a[i].w};
; #pragma unroll
;         for (int e = 0; e < 4; ++e) {
;           float lo = __uint_as_float(a[e] << 16), hi = __uint_as_float(a[e] & 0xffff0000u);
;           ss[i] += lo * lo + hi * hi;
;         }
;       }
;     }
;     __syncthreads();
;     if (kt + 2 < nk) gl(R, kt + 2);
;     __builtin_amdgcn_sched_barrier(0);
; #pragma unroll
;     for (int kh = 0; kh < 2; ++kh) {
;       bf16x8 af[2][2], bfr[2][2];
; #pragma unroll
;       for (int ks = 0; ks < 2; ++ks) {
; #pragma unroll
;         for (int i = 0; i < 2; ++i) af[ks][i] = *(const bf16x8*)(As + aofs + i * 32 * 72 + (kh * 2 + ks) * 16);
; #pragma unroll
;         for (int j = 0; j < 2; ++j) bfr[ks][j] = *(const bf16x8*)(Bs + bofs + j * 32 * 72 + (kh * 2 + ks) * 16);
;       }
; #pragma unroll
;       for (int ks = 0; ks < 2; ++ks)
; #pragma unroll
;         for (int i = 0; i < 2; ++i)
; #pragma unroll
;           for (int j = 0; j < 2; ++j)
;             acc[i][j] = __builtin_amdgcn_mfma_f32_32x32x16_bf16(af[ks][i], bfr[ks][j], acc[i][j], 0, 0, 0);
	ds_write_b128 v157, v[102:105]
	ds_write_b128 v157, v[106:109] offset:18432
	ds_write_b128 v157, v[90:93] offset:4608
	ds_write_b128 v157, v[114:117] offset:23040
	ds_write_b128 v157, v[74:77] offset:9216
	ds_write_b128 v157, v[134:137] offset:27648
	ds_write_b128 v157, v[66:69] offset:13824
	ds_write_b128 v157, v[138:141] offset:32256
	v_lshlrev_b32_e32 v106, 16, v102
	v_and_b32_e32 v102, 0xffff0000, v102
	v_mul_f32_e32 v102, v102, v102
	v_fmac_f32_e32 v102, v106, v106
	v_lshlrev_b32_e32 v106, 16, v103
	v_and_b32_e32 v103, 0xffff0000, v103
	v_mul_f32_e32 v103, v103, v103
	v_add_f32_e32 v102, v159, v102
	v_fmac_f32_e32 v103, v106, v106
	v_add_f32_e32 v102, v103, v102
	v_lshlrev_b32_e32 v103, 16, v104
	v_and_b32_e32 v104, 0xffff0000, v104
	v_mul_f32_e32 v104, v104, v104
	v_fmac_f32_e32 v104, v103, v103
	v_add_f32_e32 v102, v104, v102
	v_and_b32_e32 v104, 0xffff0000, v105
	v_lshlrev_b32_e32 v103, 16, v105
	v_mul_f32_e32 v104, v104, v104
	v_fmac_f32_e32 v104, v103, v103
	v_add_f32_e32 v159, v104, v102
	s_waitcnt lgkmcnt(0)
	s_barrier
	global_load_dwordx4 v[134:137], v[142:143], off offset:384
	global_load_dwordx4 v[138:141], v[144:145], off offset:384
	global_load_dwordx4 v[114:117], v[146:147], off offset:384
	s_nop 0
	global_load_dwordx4 v[142:145], v[148:149], off offset:384
	global_load_dwordx4 v[106:109], v[150:151], off offset:384
	s_nop 0
	global_load_dwordx4 v[146:149], v[152:153], off offset:384
	global_load_dwordx4 v[102:105], v[160:161], off offset:384
	s_nop 0
	global_load_dwordx4 v[150:153], v[162:163], off offset:384
	ds_read_b128 v[188:191], v158
	ds_read_b128 v[228:231], v154 offset:18432
	ds_read_b128 v[232:235], v154 offset:23040
	ds_read_b128 v[192:195], v158 offset:4608
	ds_read_b128 v[200:203], v158 offset:32
	ds_read_b128 v[236:239], v154 offset:18464
	ds_read_b128 v[240:243], v154 offset:23072
	ds_read_b128 v[204:207], v158 offset:4640
	s_waitcnt lgkmcnt(6)
	v_mfma_f32_32x32x16_bf16 v[34:49], v[188:191], v[228:231], v[34:49]
	s_waitcnt lgkmcnt(5)
	v_mfma_f32_32x32x16_bf16 v[50:65], v[188:191], v[232:235], v[50:65]
	s_waitcnt lgkmcnt(4)
	v_mfma_f32_32x32x16_bf16 v[2:17], v[192:195], v[228:231], v[2:17]
	v_mfma_f32_32x32x16_bf16 v[18:33], v[192:195], v[232:235], v[18:33]
	ds_read_b128 v[188:191], v158 offset:64
	ds_read_b128 v[228:231], v154 offset:18496
	ds_read_b128 v[232:235], v154 offset:23104
	ds_read_b128 v[192:195], v158 offset:4672
	s_waitcnt lgkmcnt(6)
	v_mfma_f32_32x32x16_bf16 v[34:49], v[200:203], v[236:239], v[34:49]
	s_waitcnt lgkmcnt(5)
	v_mfma_f32_32x32x16_bf16 v[50:65], v[200:203], v[240:243], v[50:65]
	s_waitcnt lgkmcnt(4)
	v_mfma_f32_32x32x16_bf16 v[2:17], v[204:207], v[236:239], v[2:17]
	v_mfma_f32_32x32x16_bf16 v[18:33], v[204:207], v[240:243], v[18:33]
	ds_read_b128 v[200:203], v158 offset:96
	ds_read_b128 v[236:239], v154 offset:18528
	ds_read_b128 v[240:243], v154 offset:23136
	ds_read_b128 v[204:207], v158 offset:4704
	s_waitcnt lgkmcnt(6)
	v_mfma_f32_32x32x16_bf16 v[34:49], v[188:191], v[228:231], v[34:49]
	s_waitcnt lgkmcnt(5)
	v_mfma_f32_32x32x16_bf16 v[50:65], v[188:191], v[232:235], v[50:65]
	s_waitcnt lgkmcnt(4)
	v_mfma_f32_32x32x16_bf16 v[2:17], v[192:195], v[228:231], v[2:17]
	v_mfma_f32_32x32x16_bf16 v[18:33], v[192:195], v[232:235], v[18:33]
	s_waitcnt lgkmcnt(2)
	v_mfma_f32_32x32x16_bf16 v[34:49], v[200:203], v[236:239], v[34:49]
	s_waitcnt lgkmcnt(1)
	v_mfma_f32_32x32x16_bf16 v[50:65], v[200:203], v[240:243], v[50:65]
	s_waitcnt lgkmcnt(0)
	v_mfma_f32_32x32x16_bf16 v[2:17], v[204:207], v[236:239], v[2:17]
	v_mfma_f32_32x32x16_bf16 v[18:33], v[204:207], v[240:243], v[18:33]
	s_barrier
	s_waitcnt vmcnt(15)
	ds_write_b128 v157, v[110:113]
	s_waitcnt vmcnt(14)
	ds_write_b128 v157, v[118:121] offset:18432
	s_waitcnt vmcnt(13)
	ds_write_b128 v157, v[98:101] offset:4608
	s_waitcnt vmcnt(12)
	ds_write_b128 v157, v[122:125] offset:23040
	s_waitcnt vmcnt(11)
	ds_write_b128 v157, v[94:97] offset:9216
	s_waitcnt vmcnt(10)
	ds_write_b128 v157, v[126:129] offset:27648
	s_waitcnt vmcnt(9)
	ds_write_b128 v157, v[82:85] offset:13824
	s_waitcnt vmcnt(8)
	ds_write_b128 v157, v[130:133] offset:32256
	s_waitcnt lgkmcnt(0)
	s_barrier
; template <bool ROWRMS>
; __device__ __forceinline__ void gemm_mainloop(const u16* __restrict__ A, int lda, const u16* __restrict__ Bt, int ldb,
;                                               int K, f32x16 (&acc)[2][2], char* smem, float* rs) {
;     ...
;   auto step = [&](GRegs& R, int kt) {
;     __syncthreads();
; #pragma unroll
;     for (int i = 0; i < 4; ++i) {
;       *(u32x4*)(As + wofs + i * 32 * 72) = R.a[i];
;       *(u32x4*)(Bs + wofs + i * 32 * 72) = R.b[i];
;     }
;     if (ROWRMS) {
; #pragma unroll
;       for (int i = 0; i < 4; ++i) {
;         unsigned a[4] = {R.a[i].x, R.a[i].y, R.a[i].z, R.a[i].w};
; #pragma unroll
;         for (int e = 0; e < 4; ++e) {
;           float lo = __uint_as_float(a[e] << 16), hi = __uint_as_float(a[e] & 0xffff0000u);
;           ss[i] += lo * lo + hi * hi;
;         }
;       }
;     }
;     __syncthreads();
;     if (kt + 2 < nk) gl(R, kt + 2);
;     __builtin_amdgcn_sched_barrier(0);
; #pragma unroll
;     for (int kh = 0; kh < 2; ++kh) {
;       bf16x8 af[2][2], bfr[2][2];
; #pragma unroll
;       for (int ks = 0; ks < 2; ++ks) {
; #pragma unroll
;         for (int i = 0; i < 2; ++i) af[ks][i] = *(const bf16x8*)(As + aofs + i * 32 * 72 + (kh * 2 + ks) * 16);
; #pragma unroll
;         for (int j = 0; j < 2; ++j) bfr[ks][j] = *(const bf16x8*)(Bs + bofs + j * 32 * 72 + (kh * 2 + ks) * 16);
;       }
; #pragma unroll
;       for (int ks = 0; ks < 2; ++ks)
; #pragma unroll
;         for (int i = 0; i < 2; ++i)
; #pragma unroll
;           for (int j = 0; j < 2; ++j)
;             acc[i][j] = __builtin_amdgcn_mfma_f32_32x32x16_bf16(af[ks][i], bfr[ks][j], acc[i][j], 0, 0, 0);
;     }
;     __builtin_amdgcn_sched_barrier(0);
;   };
;   GRegs R0, R1;
;   gl(R0, 0);
;   gl(R1, 1);
;   for (int kt = 0; kt < nk; kt += 2) {
;     step(R0, kt);
;     step(R1, kt + 1);
;   }
;   if (ROWRMS) {
; #pragma unroll
;     for (int i = 0; i < 4; ++i) {
;       float v = ss[i];
;       v += __shfl_xor(v, 1); v += __shfl_xor(v, 2); v += __shfl_xor(v, 4);
;       if ((tid & 7) == 0) rs[r0 + 32 * i] = rsqrtf(v / (float)K + EPS);
;     }
;   }
	ds_read_b128 v[188:191], v158
	ds_read_b128 v[228:231], v154 offset:18432
	ds_read_b128 v[232:235], v154 offset:23040
	ds_read_b128 v[192:195], v158 offset:4608
	ds_read_b128 v[200:203], v158 offset:32
	ds_read_b128 v[236:239], v154 offset:18464
	ds_read_b128 v[240:243], v154 offset:23072
	ds_read_b128 v[204:207], v158 offset:4640
	s_waitcnt lgkmcnt(6)
	v_mfma_f32_32x32x16_bf16 v[34:49], v[188:191], v[228:231], v[34:49]
	s_waitcnt lgkmcnt(5)
	v_mfma_f32_32x32x16_bf16 v[50:65], v[188:191], v[232:235], v[50:65]
	s_waitcnt lgkmcnt(4)
	v_mfma_f32_32x32x16_bf16 v[2:17], v[192:195], v[228:231], v[2:17]
	v_mfma_f32_32x32x16_bf16 v[18:33], v[192:195], v[232:235], v[18:33]
	ds_read_b128 v[188:191], v158 offset:64
	ds_read_b128 v[228:231], v154 offset:18496
	ds_read_b128 v[232:235], v154 offset:23104
	ds_read_b128 v[192:195], v158 offset:4672
	s_waitcnt lgkmcnt(6)
	v_mfma_f32_32x32x16_bf16 v[34:49], v[200:203], v[236:239], v[34:49]
	s_waitcnt lgkmcnt(5)
	v_mfma_f32_32x32x16_bf16 v[50:65], v[200:203], v[240:243], v[50:65]
	s_waitcnt lgkmcnt(4)
	v_mfma_f32_32x32x16_bf16 v[2:17], v[204:207], v[236:239], v[2:17]
	v_mfma_f32_32x32x16_bf16 v[18:33], v[204:207], v[240:243], v[18:33]
	ds_read_b128 v[200:203], v158 offset:96
	ds_read_b128 v[236:239], v154 offset:18528
	ds_read_b128 v[240:243], v154 offset:23136
	ds_read_b128 v[204:207], v158 offset:4704
	s_waitcnt lgkmcnt(6)
	v_mfma_f32_32x32x16_bf16 v[34:49], v[188:191], v[228:231], v[34:49]
	s_waitcnt lgkmcnt(5)
	v_mfma_f32_32x32x16_bf16 v[50:65], v[188:191], v[232:235], v[50:65]
	s_waitcnt lgkmcnt(4)
	v_mfma_f32_32x32x16_bf16 v[2:17], v[192:195], v[228:231], v[2:17]
	v_mfma_f32_32x32x16_bf16 v[18:33], v[192:195], v[232:235], v[18:33]
	s_waitcnt lgkmcnt(2)
	v_mfma_f32_32x32x16_bf16 v[34:49], v[200:203], v[236:239], v[34:49]
	s_waitcnt lgkmcnt(1)
	v_mfma_f32_32x32x16_bf16 v[50:65], v[200:203], v[240:243], v[50:65]
	s_waitcnt lgkmcnt(0)
	v_mfma_f32_32x32x16_bf16 v[2:17], v[204:207], v[236:239], v[2:17]
	v_mfma_f32_32x32x16_bf16 v[18:33], v[204:207], v[240:243], v[18:33]
	s_waitcnt vmcnt(7)
	v_and_b32_e32 v119, 0xffff0000, v137
	v_lshlrev_b32_e32 v118, 16, v137
	v_mul_f32_e32 v119, v119, v119
	v_and_b32_e32 v120, 0xffff0000, v136
	v_fmac_f32_e32 v119, v118, v118
	v_lshlrev_b32_e32 v118, 16, v136
	v_mul_f32_e32 v120, v120, v120
	v_and_b32_e32 v121, 0xffff0000, v135
	v_fmac_f32_e32 v120, v118, v118
	v_lshlrev_b32_e32 v118, 16, v135
	v_mul_f32_e32 v121, v121, v121
	v_and_b32_e32 v122, 0xffff0000, v134
	v_fmac_f32_e32 v121, v118, v118
	v_lshlrev_b32_e32 v118, 16, v134
	v_mul_f32_e32 v122, v122, v122
	v_fmac_f32_e32 v122, v118, v118
	v_lshlrev_b32_e32 v118, 16, v113
	v_and_b32_e32 v113, 0xffff0000, v113
	v_mul_f32_e32 v113, v113, v113
	v_fmac_f32_e32 v113, v118, v118
	v_lshlrev_b32_e32 v118, 16, v112
	v_and_b32_e32 v112, 0xffff0000, v112
	v_mul_f32_e32 v112, v112, v112
	v_fmac_f32_e32 v112, v118, v118
	v_lshlrev_b32_e32 v118, 16, v111
	v_and_b32_e32 v111, 0xffff0000, v111
	v_mul_f32_e32 v111, v111, v111
	v_fmac_f32_e32 v111, v118, v118
	v_lshlrev_b32_e32 v118, 16, v110
	v_and_b32_e32 v110, 0xffff0000, v110
	v_mul_f32_e32 v110, v110, v110
	v_fmac_f32_e32 v110, v118, v118
	v_add_f32_e32 v110, v159, v110
	v_add_f32_e32 v110, v111, v110
	v_add_f32_e32 v110, v112, v110
	v_add_f32_e32 v110, v113, v110
	v_add_f32_e32 v110, v110, v122
	v_add_f32_e32 v110, v121, v110
	v_add_f32_e32 v110, v120, v110
	s_barrier
	ds_write_b128 v157, v[134:137]
	s_waitcnt vmcnt(6)
	ds_write_b128 v157, v[138:141] offset:18432
	s_waitcnt vmcnt(5)
	ds_write_b128 v157, v[114:117] offset:4608
	s_waitcnt vmcnt(4)
	ds_write_b128 v157, v[142:145] offset:23040
	s_waitcnt vmcnt(3)
	ds_write_b128 v157, v[106:109] offset:9216
	s_waitcnt vmcnt(2)
	ds_write_b128 v157, v[146:149] offset:27648
	s_waitcnt vmcnt(1)
	ds_write_b128 v157, v[102:105] offset:13824
	s_waitcnt vmcnt(0)
	ds_write_b128 v157, v[150:153] offset:32256
	s_waitcnt lgkmcnt(0)
	s_barrier
	v_add_f32_e32 v126, v119, v110
	ds_read_b128 v[188:191], v158
	ds_read_b128 v[228:231], v154 offset:18432
	ds_read_b128 v[232:235], v154 offset:23040
	ds_read_b128 v[192:195], v158 offset:4608
	ds_read_b128 v[200:203], v158 offset:32
	ds_read_b128 v[236:239], v154 offset:18464
	ds_read_b128 v[240:243], v154 offset:23072
	ds_read_b128 v[204:207], v158 offset:4640
	s_waitcnt lgkmcnt(6)
	v_mfma_f32_32x32x16_bf16 v[34:49], v[188:191], v[228:231], v[34:49]
	s_waitcnt lgkmcnt(5)
	v_mfma_f32_32x32x16_bf16 v[50:65], v[188:191], v[232:235], v[50:65]
	s_waitcnt lgkmcnt(4)
	v_mfma_f32_32x32x16_bf16 v[2:17], v[192:195], v[228:231], v[2:17]
	v_mfma_f32_32x32x16_bf16 v[18:33], v[192:195], v[232:235], v[18:33]
	ds_read_b128 v[188:191], v158 offset:64
	ds_read_b128 v[228:231], v154 offset:18496
	ds_read_b128 v[232:235], v154 offset:23104
	ds_read_b128 v[192:195], v158 offset:4672
	s_waitcnt lgkmcnt(6)
	v_mfma_f32_32x32x16_bf16 v[34:49], v[200:203], v[236:239], v[34:49]
	s_waitcnt lgkmcnt(5)
	v_mfma_f32_32x32x16_bf16 v[50:65], v[200:203], v[240:243], v[50:65]
	s_waitcnt lgkmcnt(4)
	v_mfma_f32_32x32x16_bf16 v[2:17], v[204:207], v[236:239], v[2:17]
	v_mfma_f32_32x32x16_bf16 v[18:33], v[204:207], v[240:243], v[18:33]
	ds_read_b128 v[200:203], v158 offset:96
	ds_read_b128 v[236:239], v154 offset:18528
	ds_read_b128 v[240:243], v154 offset:23136
	ds_read_b128 v[204:207], v158 offset:4704
	s_waitcnt lgkmcnt(6)
	v_mfma_f32_32x32x16_bf16 v[34:49], v[188:191], v[228:231], v[34:49]
	s_waitcnt lgkmcnt(5)
	v_mfma_f32_32x32x16_bf16 v[50:65], v[188:191], v[232:235], v[50:65]
	s_waitcnt lgkmcnt(4)
	v_mfma_f32_32x32x16_bf16 v[2:17], v[192:195], v[228:231], v[2:17]
	v_mfma_f32_32x32x16_bf16 v[18:33], v[192:195], v[232:235], v[18:33]
	s_waitcnt lgkmcnt(2)
	v_mfma_f32_32x32x16_bf16 v[34:49], v[200:203], v[236:239], v[34:49]
	s_waitcnt lgkmcnt(1)
	v_mfma_f32_32x32x16_bf16 v[50:65], v[200:203], v[240:243], v[50:65]
	s_waitcnt lgkmcnt(0)
	v_mfma_f32_32x32x16_bf16 v[2:17], v[204:207], v[236:239], v[2:17]
	v_mfma_f32_32x32x16_bf16 v[18:33], v[204:207], v[240:243], v[18:33]
	v_cmp_lt_i32_e32 vcc, v208, v209
	s_nop 1
	v_cndmask_b32_e32 v110, v199, v208, vcc
	v_cmp_lt_i32_e32 vcc, v210, v209
	v_lshlrev_b32_e32 v215, 2, v110
	s_nop 0
	v_cndmask_b32_e32 v110, v199, v210, vcc
	v_cmp_lt_i32_e32 vcc, v211, v209
	v_lshlrev_b32_e32 v214, 2, v110
	s_nop 0
	v_cndmask_b32_e32 v110, v199, v211, vcc
	v_lshlrev_b32_e32 v213, 2, v110
	ds_bpermute_b32 v110, v215, v126
	v_cmp_eq_u32_e32 vcc, 0, v164
	s_waitcnt lgkmcnt(0)
	v_add_f32_e32 v110, v126, v110
	ds_bpermute_b32 v111, v214, v110
	s_waitcnt lgkmcnt(0)
	v_add_f32_e32 v111, v110, v111
	ds_bpermute_b32 v112, v213, v111
	v_lshlrev_b32_e32 v110, 2, v156
	s_and_saveexec_b64 s[8:9], vcc
	s_cbranch_execz .LBB0_736
	s_waitcnt lgkmcnt(0)
	v_add_f32_e32 v111, v111, v112
	v_fmamk_f32 v111, v111, 0x3b800000, v1
	v_mul_f32_e32 v112, 0x4b800000, v111
	v_cmp_gt_f32_e64 s[6:7], s85, v111
	s_nop 1
	v_cndmask_b32_e64 v111, v111, v112, s[6:7]
	v_rsq_f32_e32 v111, v111
	s_nop 0
	v_mul_f32_e32 v112, 0x45800000, v111
	v_cndmask_b32_e64 v111, v111, v112, s[6:7]
	ds_write_b32 v110, v111 offset:40960

; template <bool ROWRMS>
; __device__ __forceinline__ void gemm_mainloop(const u16* __restrict__ A, int lda, const u16* __restrict__ Bt, int ldb,
;                                               int K, f32x16 (&acc)[2][2], char* smem, float* rs) {
;   const int tid = tid_opaque(), lane = tid & 63, w = tid >> 6, wm = w >> 1, wn = w & 1;
;   u16* As = (u16*)smem;
;   u16* Bs = As + 128 * 72;
;   const int r0 = tid >> 3, kc = (tid & 7) * 8;
;   const u16* ga = A + (long)r0 * lda + kc;
;   const u16* gb = Bt + (long)r0 * ldb + kc;
;   const long a32 = 32L * lda, b32 = 32L * ldb;
;   float ss[4] = {0.f, 0.f, 0.f, 0.f};
; #pragma unroll
;   for (int i = 0; i < 2; ++i)
; #pragma unroll
;     for (int j = 0; j < 2; ++j)
; #pragma unroll
;       for (int r = 0; r < 16; ++r) acc[i][j][r] = 0.f;
;   const int nk = K >> 6;
;   const int wofs = r0 * 72 + kc;
;   const int aofs = (wm * 64 + (lane & 31)) * 72 + (lane >> 5) * 8;
;   const int bofs = (wn * 64 + (lane & 31)) * 72 + (lane >> 5) * 8;
;   auto gl = [&](GRegs& R, int kt) {
;     const int ko = kt * 64;
; #pragma unroll
;     for (int i = 0; i < 4; ++i) {
;       R.a[i] = *(const u32x4*)(ga + i * a32 + ko);
;       R.b[i] = *(const u32x4*)(gb + i * b32 + ko);
;     }
;   };
;   auto step = [&](GRegs& R, int kt) {
;     __syncthreads();
; #pragma unroll
;     for (int i = 0; i < 4; ++i) {
;       *(u32x4*)(As + wofs + i * 32 * 72) = R.a[i];
;       *(u32x4*)(Bs + wofs + i * 32 * 72) = R.b[i];
;     }
;     if (ROWRMS) {
; #pragma unroll
;       for (int i = 0; i < 4; ++i) {
;         unsigned a[4] = {R.a[i].x, R.a[i].y, R.a[i].z, R.a[i].w};
; #pragma unroll
;         for (int e = 0; e < 4; ++e) {
;           float lo = __uint_as_float(a[e] << 16), hi = __uint_as_float(a[e] & 0xffff0000u);
;           ss[i] += lo * lo + hi * hi;
;         }
;       }
;     }
;     __syncthreads();
;     if (kt + 2 < nk) gl(R, kt + 2);
;     __builtin_amdgcn_sched_barrier(0);
; #pragma unroll
;     for (int kh = 0; kh < 2; ++kh) {
;       bf16x8 af[2][2], bfr[2][2];
; #pragma unroll
;       for (int ks = 0; ks < 2; ++ks) {
; #pragma unroll
; __device__ __forceinline__ void phaseB(const P& p, int l, char* smem, unsigned* ctr) {
;     ...
;       int mt = e >> 2, nt = e & 3;
;       gemm_mainloop<false>(p.ckv + (long)mt * 128 * 128, 128, p.wt_kv + ((long)l * 512 + nt * 128) * 128, 128, 128, acc, smem, nullptr);
.LBB0_755:
	s_load_dwordx4 s[24:27], s[28:29], 0x1a0
	s_ashr_i32 s6, s38, 2
	s_ashr_i32 s7, s6, 31
	s_and_b32 s91, s38, 3
	s_lshl_b64 s[8:9], s[6:7], 15
	s_waitcnt lgkmcnt(0)
	s_add_u32 s8, s24, s8
	v_mov_b32_e32 v44, v198
	s_addc_u32 s9, s25, s9
	s_lshl_b32 s0, s91, 15
	s_add_u32 s22, s56, s0
	v_ashrrev_i32_e32 v34, 3, v44
	v_lshlrev_b32_e32 v2, 3, v44
	v_ashrrev_i32_e32 v35, 31, v34
	s_addc_u32 s23, s57, 0
	v_and_b32_e32 v45, 56, v2
	v_lshlrev_b64 v[2:3], 8, v[34:35]
	v_lshl_add_u64 v[4:5], s[22:23], 0, v[2:3]
	v_lshlrev_b32_e32 v154, 1, v45
	v_lshl_add_u64 v[38:39], v[4:5], 0, v[154:155]
	v_lshl_add_u64 v[2:3], s[8:9], 0, v[2:3]
	v_add_co_u32_e32 v30, vcc, s89, v38
	v_lshl_add_u64 v[36:37], v[2:3], 0, v[154:155]
	s_nop 0
	v_addc_co_u32_e32 v31, vcc, 0, v39, vcc
	v_add_co_u32_e32 v2, vcc, s89, v36
	v_and_b32_e32 v35, 0x5f, v44
	s_nop 0
	v_addc_co_u32_e32 v3, vcc, 0, v37, vcc
	v_add_co_u32_e32 v18, vcc, s17, v38
	s_nop 1
	v_addc_co_u32_e32 v19, vcc, 0, v39, vcc
	v_add_co_u32_e32 v6, vcc, s17, v36
	s_nop 1
	v_addc_co_u32_e32 v7, vcc, 0, v37, vcc
	v_add_co_u32_e32 v40, vcc, s90, v38
	s_nop 1
	v_addc_co_u32_e32 v41, vcc, 0, v39, vcc
	v_add_co_u32_e32 v42, vcc, s90, v36
	s_nop 1
	v_addc_co_u32_e32 v43, vcc, 0, v37, vcc
	global_load_dwordx4 v[66:69], v[2:3], off offset:128
	s_nop 0
	global_load_dwordx4 v[2:5], v[2:3], off
	s_nop 0
	global_load_dwordx4 v[70:73], v[6:7], off offset:128
	s_nop 0
	global_load_dwordx4 v[6:9], v[6:7], off
	s_nop 0
	global_load_dwordx4 v[10:13], v[36:37], off
	global_load_dwordx4 v[14:17], v[42:43], off
	global_load_dwordx4 v[74:77], v[18:19], off offset:128
	s_nop 0
	global_load_dwordx4 v[18:21], v[18:19], off
	s_nop 0
	global_load_dwordx4 v[22:25], v[38:39], off
	global_load_dwordx4 v[26:29], v[40:41], off
	global_load_dwordx4 v[78:81], v[30:31], off offset:128
	s_nop 0
	global_load_dwordx4 v[30:33], v[30:31], off
	s_nop 0
	global_load_dwordx4 v[82:85], v[42:43], off offset:128
	global_load_dwordx4 v[86:89], v[38:39], off offset:128
	global_load_dwordx4 v[90:93], v[36:37], off offset:128
	global_load_dwordx4 v[94:97], v[40:41], off offset:128
	v_lshrrev_b32_e32 v36, 1, v44
	v_and_b32_e32 v37, 31, v44
	v_and_or_b32 v37, v36, s15, v37
	v_mul_lo_u32 v38, v34, s13
	v_and_b32_e32 v34, 16, v36
	v_add_lshl_u32 v112, v38, v45, 1
	v_mad_u64_u32 v[110:111], s[8:9], v37, s84, v[34:35]
	v_mad_u32_u24 v111, v35, s84, v34
	s_waitcnt vmcnt(63) expcnt(7) lgkmcnt(15)
	s_barrier
	s_waitcnt vmcnt(0)
	ds_write_b128 v112, v[10:13]
	ds_write_b128 v112, v[14:17] offset:4608
	ds_write_b128 v112, v[6:9] offset:9216
	ds_write_b128 v112, v[2:5] offset:13824
	ds_write_b128 v112, v[22:25] offset:18432
	ds_write_b128 v112, v[26:29] offset:23040
	ds_write_b128 v112, v[18:21] offset:27648
	ds_write_b128 v112, v[30:33] offset:32256
	s_waitcnt lgkmcnt(0)
	s_barrier
	ds_read_b128 v[2:5], v110
	ds_read_b128 v[6:9], v111 offset:18432
	ds_read_b128 v[18:21], v111 offset:23040
	ds_read_b128 v[22:25], v110 offset:4608
	ds_read_b128 v[98:101], v110 offset:32
	ds_read_b128 v[102:105], v111 offset:18464
	ds_read_b128 v[106:109], v111 offset:23072
	s_waitcnt lgkmcnt(5)
	v_mfma_f32_32x32x16_bf16 v[34:49], v[2:5], v[6:9], 0
	s_waitcnt lgkmcnt(4)
	v_mfma_f32_32x32x16_bf16 v[50:65], v[2:5], v[18:21], 0
	s_waitcnt lgkmcnt(1)
	v_mfma_f32_32x32x16_bf16 v[34:49], v[98:101], v[102:105], v[34:49]
	s_waitcnt lgkmcnt(0)
	v_mfma_f32_32x32x16_bf16 v[50:65], v[98:101], v[106:109], v[50:65]
	ds_read_b128 v[98:101], v110 offset:4640
	v_mfma_f32_32x32x16_bf16 v[2:17], v[22:25], v[6:9], 0
	v_mfma_f32_32x32x16_bf16 v[18:33], v[22:25], v[18:21], 0
	s_waitcnt lgkmcnt(0)
	v_mfma_f32_32x32x16_bf16 v[2:17], v[98:101], v[102:105], v[2:17]
	v_mfma_f32_32x32x16_bf16 v[18:33], v[98:101], v[106:109], v[18:33]
	ds_read_b128 v[98:101], v110 offset:64
	ds_read_b128 v[102:105], v111 offset:18496
	ds_read_b128 v[106:109], v111 offset:23104
	s_waitcnt lgkmcnt(1)
	v_mfma_f32_32x32x16_bf16 v[34:49], v[98:101], v[102:105], v[34:49]
	s_waitcnt lgkmcnt(0)
	v_mfma_f32_32x32x16_bf16 v[50:65], v[98:101], v[106:109], v[50:65]
	ds_read_b128 v[98:101], v110 offset:4672
	s_waitcnt lgkmcnt(0)
	v_mfma_f32_32x32x16_bf16 v[2:17], v[98:101], v[102:105], v[2:17]
	v_mfma_f32_32x32x16_bf16 v[18:33], v[98:101], v[106:109], v[18:33]
	ds_read_b128 v[98:101], v110 offset:96
	ds_read_b128 v[102:105], v111 offset:18528
	ds_read_b128 v[106:109], v111 offset:23136
	s_waitcnt lgkmcnt(1)
	v_mfma_f32_32x32x16_bf16 v[34:49], v[98:101], v[102:105], v[34:49]
	s_waitcnt lgkmcnt(0)
	v_mfma_f32_32x32x16_bf16 v[50:65], v[98:101], v[106:109], v[50:65]
	ds_read_b128 v[98:101], v110 offset:4704
	s_waitcnt lgkmcnt(0)
	v_mfma_f32_32x32x16_bf16 v[2:17], v[98:101], v[102:105], v[2:17]
	v_mfma_f32_32x32x16_bf16 v[18:33], v[98:101], v[106:109], v[18:33]
	s_barrier
	ds_write_b128 v112, v[90:93]
	ds_write_b128 v112, v[86:89] offset:18432
	ds_write_b128 v112, v[82:85] offset:4608
	ds_write_b128 v112, v[94:97] offset:23040
	ds_write_b128 v112, v[70:73] offset:9216
	ds_write_b128 v112, v[74:77] offset:27648
	ds_write_b128 v112, v[66:69] offset:13824
	ds_write_b128 v112, v[78:81] offset:32256
	s_waitcnt lgkmcnt(0)
	s_barrier
; template <bool ROWRMS>
; __device__ __forceinline__ void gemm_mainloop(const u16* __restrict__ A, int lda, const u16* __restrict__ Bt, int ldb,
;                                               int K, f32x16 (&acc)[2][2], char* smem, float* rs) {
;     ...
; #pragma unroll
;     for (int kh = 0; kh < 2; ++kh) {
;       bf16x8 af[2][2], bfr[2][2];
; #pragma unroll
;       for (int ks = 0; ks < 2; ++ks) {
; #pragma unroll
;         for (int i = 0; i < 2; ++i) af[ks][i] = *(const bf16x8*)(As + aofs + i * 32 * 72 + (kh * 2 + ks) * 16);
; #pragma unroll
;         for (int j = 0; j < 2; ++j) bfr[ks][j] = *(const bf16x8*)(Bs + bofs + j * 32 * 72 + (kh * 2 + ks) * 16);
;       }
; #pragma unroll
;       for (int ks = 0; ks < 2; ++ks)
; #pragma unroll
;         for (int i = 0; i < 2; ++i)
; #pragma unroll
;           for (int j = 0; j < 2; ++j)
;             acc[i][j] = __builtin_amdgcn_mfma_f32_32x32x16_bf16(af[ks][i], bfr[ks][j], acc[i][j], 0, 0, 0);
;     }
; __device__ __forceinline__ void stage_c(const f32x16 (&acc)[2][2], int half, float* Cs) {
;   const int tid = tid_opaque(), lane = tid & 63, w = tid >> 6, wm = w >> 1, wn = w & 1;
;   if (wm == half) {
; #pragma unroll
;     for (int i = 0; i < 2; ++i)
; #pragma unroll
;       for (int j = 0; j < 2; ++j)
; #pragma unroll
;         for (int r = 0; r < 16; ++r) {
;           int row = i * 32 + (r & 3) + 8 * (r >> 2) + 4 * (lane >> 5);
;           int col = wn * 64 + j * 32 + (lane & 31);
;           Cs[row * 132 + col] = acc[i][j][r];
;         }
;   }
; }
	ds_read_b128 v[188:191], v110
	ds_read_b128 v[228:231], v111 offset:18432
	ds_read_b128 v[232:235], v111 offset:23040
	ds_read_b128 v[192:195], v110 offset:4608
	ds_read_b128 v[200:203], v110 offset:32
	ds_read_b128 v[236:239], v111 offset:18464
	ds_read_b128 v[240:243], v111 offset:23072
	ds_read_b128 v[204:207], v110 offset:4640
	s_waitcnt lgkmcnt(6)
	v_mfma_f32_32x32x16_bf16 v[34:49], v[188:191], v[228:231], v[34:49]
	s_waitcnt lgkmcnt(5)
	v_mfma_f32_32x32x16_bf16 v[50:65], v[188:191], v[232:235], v[50:65]
	s_waitcnt lgkmcnt(4)
	v_mfma_f32_32x32x16_bf16 v[2:17], v[192:195], v[228:231], v[2:17]
	v_mfma_f32_32x32x16_bf16 v[18:33], v[192:195], v[232:235], v[18:33]
	ds_read_b128 v[188:191], v110 offset:64
	ds_read_b128 v[228:231], v111 offset:18496
	ds_read_b128 v[232:235], v111 offset:23104
	ds_read_b128 v[192:195], v110 offset:4672
	s_waitcnt lgkmcnt(6)
	v_mfma_f32_32x32x16_bf16 v[34:49], v[200:203], v[236:239], v[34:49]
	s_waitcnt lgkmcnt(5)
	v_mfma_f32_32x32x16_bf16 v[50:65], v[200:203], v[240:243], v[50:65]
	s_waitcnt lgkmcnt(4)
	v_mfma_f32_32x32x16_bf16 v[2:17], v[204:207], v[236:239], v[2:17]
	v_mfma_f32_32x32x16_bf16 v[18:33], v[204:207], v[240:243], v[18:33]
	ds_read_b128 v[200:203], v110 offset:96
	ds_read_b128 v[236:239], v111 offset:18528
	ds_read_b128 v[240:243], v111 offset:23136
	ds_read_b128 v[204:207], v110 offset:4704
	s_waitcnt lgkmcnt(6)
	v_mfma_f32_32x32x16_bf16 v[34:49], v[188:191], v[228:231], v[34:49]
	s_waitcnt lgkmcnt(5)
	v_mfma_f32_32x32x16_bf16 v[50:65], v[188:191], v[232:235], v[50:65]
	s_waitcnt lgkmcnt(4)
	v_mfma_f32_32x32x16_bf16 v[2:17], v[192:195], v[228:231], v[2:17]
	v_mfma_f32_32x32x16_bf16 v[18:33], v[192:195], v[232:235], v[18:33]
	s_waitcnt lgkmcnt(2)
	v_mfma_f32_32x32x16_bf16 v[34:49], v[200:203], v[236:239], v[34:49]
	s_waitcnt lgkmcnt(1)
	v_mfma_f32_32x32x16_bf16 v[50:65], v[200:203], v[240:243], v[50:65]
	s_waitcnt lgkmcnt(0)
	v_mfma_f32_32x32x16_bf16 v[2:17], v[204:207], v[236:239], v[2:17]
	v_mfma_f32_32x32x16_bf16 v[18:33], v[204:207], v[240:243], v[18:33]
	v_mov_b32_e32 v66, v198
	s_barrier
	s_nop 0
	v_cmp_gt_u32_e32 vcc, s86, v66
	s_and_saveexec_b64 s[8:9], vcc
	s_cbranch_execz .LBB0_757
	v_lshrrev_b32_e32 v67, 3, v66
	v_and_b32_e32 v68, 0x5f, v66
	v_and_b32_e32 v67, 4, v67
	v_lshlrev_b32_e32 v68, 2, v68
	v_mad_u32_u24 v68, v67, s87, v68
	v_add_u32_e32 v69, 0x400, v68
	ds_write2_b32 v69, v36, v37 offset0:8 offset1:140
	v_add_u32_e32 v69, 0x1000, v68
	ds_write2_b32 v69, v38, v39 offset0:32 offset1:164
	v_add_u32_e32 v69, 0x1400, v68
	ds_write2_b32 v69, v40, v41 offset0:40 offset1:172
	v_add_u32_e32 v69, 0x2000, v68
	ds_write2_b32 v69, v42, v43 offset0:64 offset1:196
	v_add_u32_e32 v69, 0x2400, v68
	v_lshl_or_b32 v66, v66, 2, v212
	ds_write2_b32 v69, v44, v45 offset0:72 offset1:204
	v_add_u32_e32 v69, 0x3000, v68
	v_mad_u32_u24 v66, v67, s87, v66
	ds_write2_b32 v69, v46, v47 offset0:96 offset1:228
	v_add_u32_e32 v69, 0x3400, v68
	v_add_u32_e32 v67, 0x400, v66
	ds_write2_b32 v69, v48, v49 offset0:104 offset1:236
	ds_write2_b32 v67, v52, v53 offset0:8 offset1:140
	v_add_u32_e32 v67, 0x1000, v66
	ds_write2_b32 v67, v54, v55 offset0:32 offset1:164
	v_add_u32_e32 v67, 0x1400, v66
	ds_write2_b32 v67, v56, v57 offset0:40 offset1:172
	v_add_u32_e32 v67, 0x2000, v66
	ds_write2_b32 v67, v58, v59 offset0:64 offset1:196
	v_add_u32_e32 v67, 0x2400, v66
	ds_write2_b32 v67, v60, v61 offset0:72 offset1:204
	v_add_u32_e32 v67, 0x3000, v66
	ds_write2_b32 v67, v62, v63 offset0:96 offset1:228
	v_add_u32_e32 v67, 0x3400, v66
	ds_write2_b32 v67, v64, v65 offset0:104 offset1:236
	v_add_u32_e32 v67, 0x4200, v68
	ds_write2_b32 v68, v34, v35 offset1:132
	ds_write2_b32 v66, v50, v51 offset1:132
	ds_write2_b32 v67, v2, v3 offset1:132
	v_add_u32_e32 v67, 0x4600, v68
	ds_write2_b32 v67, v4, v5 offset0:8 offset1:140
	v_add_u32_e32 v67, 0x5200, v68
	ds_write2_b32 v67, v6, v7 offset0:32 offset1:164
	v_add_u32_e32 v67, 0x5600, v68
	ds_write2_b32 v67, v8, v9 offset0:40 offset1:172
	v_add_u32_e32 v67, 0x6200, v68
	ds_write2_b32 v67, v10, v11 offset0:64 offset1:196
	v_add_u32_e32 v67, 0x6600, v68
	ds_write2_b32 v67, v12, v13 offset0:72 offset1:204
	v_add_u32_e32 v67, 0x7200, v68
	ds_write2_b32 v67, v14, v15 offset0:96 offset1:228
	v_add_u32_e32 v67, 0x7600, v68
	ds_write2_b32 v67, v16, v17 offset0:104 offset1:236
	v_add_u32_e32 v67, 0x4200, v66
	ds_write2_b32 v67, v18, v19 offset1:132
	v_add_u32_e32 v67, 0x4600, v66
	ds_write2_b32 v67, v20, v21 offset0:8 offset1:140
	v_add_u32_e32 v67, 0x5200, v66
	ds_write2_b32 v67, v22, v23 offset0:32 offset1:164
	v_add_u32_e32 v67, 0x5600, v66
	ds_write2_b32 v67, v24, v25 offset0:40 offset1:172
	v_add_u32_e32 v67, 0x6200, v66
	ds_write2_b32 v67, v26, v27 offset0:64 offset1:196
	v_add_u32_e32 v67, 0x6600, v66
	ds_write2_b32 v67, v28, v29 offset0:72 offset1:204
	v_add_u32_e32 v67, 0x7200, v66
	v_add_u32_e32 v66, 0x7600, v66
	ds_write2_b32 v67, v30, v31 offset0:96 offset1:228
	ds_write2_b32 v66, v32, v33 offset0:104 offset1:236

; template <int DQK, int MODE> ...
;     ...
;         float rsum = 0.f;
; #pragma unroll
;         for (int ku = 0; ku < 2; ++ku)
; #pragma unroll
;           for (int r = 0; r < 16; ++r) {
;             float e = __builtin_amdgcn_exp2f(S[ku][r]);
;             S[ku][r] = e;
;             rsum += e;
;           }
;         lsum += rsum;
;     ...
; #pragma unroll
;       for (int s = 0; s < 4; ++s) {
;         const int ku = s >> 1, b = 8 * (s & 1);
;         u32x4 t;
;         t.x = pack2(S[ku][b + 0], S[ku][b + 1]);
;         t.y = pack2(S[ku][b + 2], S[ku][b + 3]);
;         t.z = pack2(S[ku][b + 4], S[ku][b + 5]);
;         t.w = pack2(S[ku][b + 6], S[ku][b + 7]);
;         pf[s] = __builtin_bit_cast(bf16x8, t);
;       }
;       if (MODE == 2) {
; #pragma unroll
;         for (int du = 0; du < 2; ++du)
; #pragma unroll
;           for (int s4 = 0; s4 < 4; ++s4) {
;             const u16* vp = Vs + (du * 32 + ql) * VST + 16 * s4 + 4 * hh;
;             u32x2 a = *(const u32x2*)vp;
;             u32x2 b = *(const u32x2*)(vp + 8);
;             vf[du][s4] = (u32x4){a.x, a.y, b.x, b.y};
;           }
;       }
; #pragma unroll
;       for (int s4 = 0; s4 < 4; ++s4)
; #pragma unroll
;         for (int du = 0; du < 2; ++du)
;           O[du] = __builtin_amdgcn_mfma_f32_32x32x16_bf16(__builtin_bit_cast(bf16x8, vf[du][s4]), pf[s4], O[du], 0, 0, 0);
.LBB0_987:
	s_setprio 1
	v_exp_f32_e32 v16, v66
	v_exp_f32_e32 v66, v67
	v_exp_f32_e32 v67, v68
	v_exp_f32_e32 v68, v69
	v_add_f32_e32 v17, 0, v16
	v_exp_f32_e32 v69, v70
	v_add_f32_e32 v17, v66, v17
	v_exp_f32_e32 v70, v71
	v_add_f32_e32 v17, v67, v17
	v_exp_f32_e32 v71, v72
	v_add_f32_e32 v17, v68, v17
	v_exp_f32_e32 v72, v73
	v_add_f32_e32 v17, v69, v17
	v_exp_f32_e32 v73, v74
	v_add_f32_e32 v17, v70, v17
	v_exp_f32_e32 v74, v75
	v_add_f32_e32 v17, v71, v17
	v_exp_f32_e32 v75, v76
	v_add_f32_e32 v17, v72, v17
	v_exp_f32_e32 v76, v77
	v_exp_f32_e32 v77, v78
	v_exp_f32_e32 v78, v79
	v_exp_f32_e32 v79, v80
	v_exp_f32_e32 v80, v81
	v_exp_f32_e32 v81, v50
	v_exp_f32_e32 v204, v51
	v_exp_f32_e32 v205, v52
	v_exp_f32_e32 v206, v53
	v_cvt_pk_bf16_f32 v50, v16, v66
	v_cvt_pk_bf16_f32 v51, v67, v68
	v_cvt_pk_bf16_f32 v52, v69, v70
	v_cvt_pk_bf16_f32 v53, v71, v72
	v_add_f32_e32 v17, v73, v17
	v_add_f32_e32 v17, v74, v17
	s_waitcnt lgkmcnt(7)
	v_mfma_f32_32x32x16_bf16 v[34:49], v[162:165], v[50:53], v[34:49]
	v_add_f32_e32 v17, v75, v17
	v_add_f32_e32 v17, v76, v17
	v_add_f32_e32 v17, v77, v17
	v_add_f32_e32 v17, v78, v17
	v_add_f32_e32 v17, v79, v17
	v_add_f32_e32 v17, v80, v17
	v_exp_f32_e32 v207, v54
	s_waitcnt lgkmcnt(3)
	v_mfma_f32_32x32x16_bf16 v[18:33], v[158:161], v[50:53], v[18:33]
	v_exp_f32_e32 v208, v55
	v_exp_f32_e32 v209, v56
	v_exp_f32_e32 v210, v57
	v_cvt_pk_bf16_f32 v54, v73, v74
	v_cvt_pk_bf16_f32 v55, v75, v76
	v_cvt_pk_bf16_f32 v56, v77, v78
	v_cvt_pk_bf16_f32 v57, v79, v80
	v_add_f32_e32 v17, v81, v17
	v_add_f32_e32 v17, v204, v17
	v_mfma_f32_32x32x16_bf16 v[34:49], v[154:157], v[54:57], v[34:49]
	v_add_f32_e32 v17, v205, v17
	v_add_f32_e32 v17, v206, v17
	v_add_f32_e32 v17, v207, v17
	v_exp_f32_e32 v211, v58
	v_add_f32_e32 v17, v208, v17
	v_exp_f32_e32 v212, v59
	v_add_f32_e32 v17, v209, v17
	s_waitcnt lgkmcnt(2)
	v_mfma_f32_32x32x16_bf16 v[18:33], v[150:153], v[54:57], v[18:33]
	v_exp_f32_e32 v213, v60
	v_add_f32_e32 v17, v210, v17
	v_exp_f32_e32 v214, v61
	v_cvt_pk_bf16_f32 v58, v81, v204
	v_cvt_pk_bf16_f32 v59, v205, v206
	v_cvt_pk_bf16_f32 v60, v207, v208
	v_cvt_pk_bf16_f32 v61, v209, v210
	v_add_f32_e32 v17, v211, v17
	v_exp_f32_e32 v215, v62
	v_mfma_f32_32x32x16_bf16 v[34:49], v[146:149], v[58:61], v[34:49]
	v_add_f32_e32 v17, v212, v17
	v_exp_f32_e32 v216, v63
	v_add_f32_e32 v17, v213, v17
	v_exp_f32_e32 v217, v64
	v_add_f32_e32 v17, v214, v17
	v_exp_f32_e32 v65, v65
	v_add_f32_e32 v17, v215, v17
	s_waitcnt lgkmcnt(1)
	v_mfma_f32_32x32x16_bf16 v[18:33], v[12:15], v[58:61], v[18:33]
	v_add_f32_e32 v17, v216, v17
	v_add_f32_e32 v17, v217, v17
	v_add_f32_e32 v17, v65, v17
	v_cvt_pk_bf16_f32 v62, v211, v212
	v_cvt_pk_bf16_f32 v63, v213, v214
	v_cvt_pk_bf16_f32 v64, v215, v216
	v_cvt_pk_bf16_f32 v65, v217, v65
	v_add_f32_e32 v177, v177, v17
	s_andn2_b64 s[0:1], s[0:1], exec
	v_mfma_f32_32x32x16_bf16 v[34:49], v[8:11], v[62:65], v[34:49]
	s_waitcnt lgkmcnt(0)
	v_mfma_f32_32x32x16_bf16 v[18:33], v[4:7], v[62:65], v[18:33]
	s_setprio 0

; template <int DQK, int MODE> ...
;     ...
;       {
;         bf16x8 kf[2][NKK];
; #pragma unroll
;         for (int ku = 0; ku < 2; ++ku)
; #pragma unroll
;           for (int kk = 0; kk < NKK; ++kk)
;             kf[ku][kk] = *(const bf16x8*)(Ks + (ku * 32 + ql) * KST + kk * 16 + hh * 8);
;         __builtin_amdgcn_sched_barrier(0);
; #pragma unroll
;         for (int ku = 0; ku < 2; ++ku)
; #pragma unroll
;           for (int r = 0; r < 16; ++r) S[ku][r] = cinit;
; #pragma unroll
;         for (int kk = 0; kk < NKK; ++kk)
; #pragma unroll
;           for (int ku = 0; ku < 2; ++ku)
;             S[ku] = __builtin_amdgcn_mfma_f32_32x32x16_bf16(kf[ku][kk], qf[kk], S[ku], 0, 0, 0);
;       }
.LBB0_992:
	s_and_saveexec_b64 s[16:17], s[18:19]
	s_cbranch_execz .Lmy_ia0_a
	ds_read_b128 v[4:7], v185
	ds_read_b128 v[8:11], v185 offset:32
	ds_read_b128 v[12:15], v185 offset:64
	ds_read_b128 v[146:149], v185 offset:96
	ds_read_b128 v[150:153], v185 offset:128
	ds_read_b128 v[154:157], v185 offset:160
	ds_read_b128 v[158:161], v185 offset:6656
	ds_read_b128 v[162:165], v185 offset:6688
	ds_read_b128 v[204:207], v185 offset:6720
	ds_read_b128 v[208:211], v185 offset:6752
	ds_read_b128 v[212:215], v185 offset:6784
	ds_read_b128 v[216:219], v185 offset:6816
	s_waitcnt lgkmcnt(11)
	v_mfma_f32_32x32x16_bf16 v[66:81], v[4:7], v[86:89], v[228:243]
	v_add_u32_e32 v4, 0x3000, v187
	s_waitcnt lgkmcnt(5)
	v_mfma_f32_32x32x16_bf16 v[50:65], v[158:161], v[86:89], v[228:243]
	s_cmp_gt_i32 s5, s2
	s_cbranch_scc1 .Lmy_w1_nl
	v_add_u32_e32 v226, 0x8e00, v184
	s_waitcnt vmcnt(9)
	ds_write_b128 v201, v[122:125] offset:23040
	s_waitcnt vmcnt(8)
	ds_write_b128 v202, v[126:129] offset:23040
	s_waitcnt vmcnt(7)
	ds_write_b128 v203, v[134:137] offset:23040
	s_waitcnt vmcnt(6)
	ds_write2_b64 v226, v[138:139], v[140:141] offset1:1
	v_add_u32_e32 v226, 0x8e00, v186
	s_waitcnt vmcnt(5)
	ds_write2_b64 v226, v[142:143], v[144:145] offset1:1
	s_branch .Lmy_w1_dn

; template <int DQK, int MODE> ...
;     ...
;         float rsum = 0.f;
; #pragma unroll
;         for (int ku = 0; ku < 2; ++ku)
; #pragma unroll
;           for (int r = 0; r < 16; ++r) {
;             float e = __builtin_amdgcn_exp2f(S[ku][r]);
;             S[ku][r] = e;
;             rsum += e;
;           }
;         lsum += rsum;
;     ...
; #pragma unroll
;       for (int s = 0; s < 4; ++s) {
;         const int ku = s >> 1, b = 8 * (s & 1);
;         u32x4 t;
;         t.x = pack2(S[ku][b + 0], S[ku][b + 1]);
;         t.y = pack2(S[ku][b + 2], S[ku][b + 3]);
;         t.z = pack2(S[ku][b + 4], S[ku][b + 5]);
;         t.w = pack2(S[ku][b + 6], S[ku][b + 7]);
;         pf[s] = __builtin_bit_cast(bf16x8, t);
;       }
;       if (MODE == 2) {
; #pragma unroll
;         for (int du = 0; du < 2; ++du)
; #pragma unroll
;           for (int s4 = 0; s4 < 4; ++s4) {
;             const u16* vp = Vs + (du * 32 + ql) * VST + 16 * s4 + 4 * hh;
;             u32x2 a = *(const u32x2*)vp;
;             u32x2 b = *(const u32x2*)(vp + 8);
;             vf[du][s4] = (u32x4){a.x, a.y, b.x, b.y};
;           }
;       }
; #pragma unroll
;       for (int s4 = 0; s4 < 4; ++s4)
; #pragma unroll
;         for (int du = 0; du < 2; ++du)
;           O[du] = __builtin_amdgcn_mfma_f32_32x32x16_bf16(__builtin_bit_cast(bf16x8, vf[du][s4]), pf[s4], O[du], 0, 0, 0);
.LBB0_995:
	s_setprio 1
	v_exp_f32_e32 v16, v66
	v_exp_f32_e32 v66, v67
	v_exp_f32_e32 v67, v68
	v_exp_f32_e32 v68, v69
	v_add_f32_e32 v17, 0, v16
	v_exp_f32_e32 v69, v70
	v_add_f32_e32 v17, v66, v17
	v_exp_f32_e32 v70, v71
	v_add_f32_e32 v17, v67, v17
	v_exp_f32_e32 v71, v72
	v_add_f32_e32 v17, v68, v17
	v_exp_f32_e32 v72, v73
	v_add_f32_e32 v17, v69, v17
	v_exp_f32_e32 v73, v74
	v_add_f32_e32 v17, v70, v17
	v_exp_f32_e32 v74, v75
	v_add_f32_e32 v17, v71, v17
	v_exp_f32_e32 v75, v76
	v_add_f32_e32 v17, v72, v17
	v_exp_f32_e32 v76, v77
	v_exp_f32_e32 v77, v78
	v_exp_f32_e32 v78, v79
	v_exp_f32_e32 v79, v80
	v_exp_f32_e32 v80, v81
	v_exp_f32_e32 v81, v50
	v_exp_f32_e32 v204, v51
	v_exp_f32_e32 v205, v52
	v_exp_f32_e32 v206, v53
	v_cvt_pk_bf16_f32 v50, v16, v66
	v_cvt_pk_bf16_f32 v51, v67, v68
	v_cvt_pk_bf16_f32 v52, v69, v70
	v_cvt_pk_bf16_f32 v53, v71, v72
	v_add_f32_e32 v17, v73, v17
	v_add_f32_e32 v17, v74, v17
	s_waitcnt lgkmcnt(7)
	v_mfma_f32_32x32x16_bf16 v[34:49], v[162:165], v[50:53], v[34:49]
	v_add_f32_e32 v17, v75, v17
	v_add_f32_e32 v17, v76, v17
	v_add_f32_e32 v17, v77, v17
	v_add_f32_e32 v17, v78, v17
	v_add_f32_e32 v17, v79, v17
	v_add_f32_e32 v17, v80, v17
	v_exp_f32_e32 v207, v54
	s_waitcnt lgkmcnt(3)
	v_mfma_f32_32x32x16_bf16 v[18:33], v[158:161], v[50:53], v[18:33]
	v_exp_f32_e32 v208, v55
	v_exp_f32_e32 v209, v56
	v_exp_f32_e32 v210, v57
	v_cvt_pk_bf16_f32 v54, v73, v74
	v_cvt_pk_bf16_f32 v55, v75, v76
	v_cvt_pk_bf16_f32 v56, v77, v78
	v_cvt_pk_bf16_f32 v57, v79, v80
	v_add_f32_e32 v17, v81, v17
	v_add_f32_e32 v17, v204, v17
	v_mfma_f32_32x32x16_bf16 v[34:49], v[154:157], v[54:57], v[34:49]
	v_add_f32_e32 v17, v205, v17
	v_add_f32_e32 v17, v206, v17
	v_add_f32_e32 v17, v207, v17
	v_exp_f32_e32 v211, v58
	v_add_f32_e32 v17, v208, v17
	v_exp_f32_e32 v212, v59
	v_add_f32_e32 v17, v209, v17
	s_waitcnt lgkmcnt(2)
	v_mfma_f32_32x32x16_bf16 v[18:33], v[150:153], v[54:57], v[18:33]
	v_exp_f32_e32 v213, v60
	v_add_f32_e32 v17, v210, v17
	v_exp_f32_e32 v214, v61
	v_cvt_pk_bf16_f32 v58, v81, v204
	v_cvt_pk_bf16_f32 v59, v205, v206
	v_cvt_pk_bf16_f32 v60, v207, v208
	v_cvt_pk_bf16_f32 v61, v209, v210
	v_add_f32_e32 v17, v211, v17
	v_exp_f32_e32 v215, v62
	v_mfma_f32_32x32x16_bf16 v[34:49], v[146:149], v[58:61], v[34:49]
	v_add_f32_e32 v17, v212, v17
	v_exp_f32_e32 v216, v63
	v_add_f32_e32 v17, v213, v17
	v_exp_f32_e32 v217, v64
	v_add_f32_e32 v17, v214, v17
	v_exp_f32_e32 v65, v65
	v_add_f32_e32 v17, v215, v17
	s_waitcnt lgkmcnt(1)
	v_mfma_f32_32x32x16_bf16 v[18:33], v[12:15], v[58:61], v[18:33]
	v_add_f32_e32 v17, v216, v17
	v_add_f32_e32 v17, v217, v17
	v_add_f32_e32 v17, v65, v17
	v_cvt_pk_bf16_f32 v62, v211, v212
	v_cvt_pk_bf16_f32 v63, v213, v214
	v_cvt_pk_bf16_f32 v64, v215, v216
	v_cvt_pk_bf16_f32 v65, v217, v65
	v_add_f32_e32 v177, v177, v17
	s_andn2_b64 s[0:1], s[0:1], exec
	v_mfma_f32_32x32x16_bf16 v[34:49], v[8:11], v[62:65], v[34:49]
	s_waitcnt lgkmcnt(0)
	v_mfma_f32_32x32x16_bf16 v[18:33], v[4:7], v[62:65], v[18:33]
	s_setprio 0
	s_branch .LBB0_996

; template <int DQK, int MODE> ...
;     ...
;       {
;         bf16x8 kf[2][NKK];
; #pragma unroll
;         for (int ku = 0; ku < 2; ++ku)
; #pragma unroll
;           for (int kk = 0; kk < NKK; ++kk)
;             kf[ku][kk] = *(const bf16x8*)(Ks + (ku * 32 + ql) * KST + kk * 16 + hh * 8);
;         __builtin_amdgcn_sched_barrier(0);
; #pragma unroll
;         for (int ku = 0; ku < 2; ++ku)
; #pragma unroll
;           for (int r = 0; r < 16; ++r) S[ku][r] = cinit;
; #pragma unroll
;         for (int kk = 0; kk < NKK; ++kk)
; #pragma unroll
;           for (int ku = 0; ku < 2; ++ku)
;             S[ku] = __builtin_amdgcn_mfma_f32_32x32x16_bf16(kf[ku][kk], qf[kk], S[ku], 0, 0, 0);
;       }
.LBB0_999:
	s_and_saveexec_b64 s[16:17], s[6:7]
	s_cbranch_execz .Lmy_ia1_a
	ds_read_b128 v[4:7], v185 offset:23040
	ds_read_b128 v[8:11], v185 offset:23072
	ds_read_b128 v[12:15], v185 offset:23104
	ds_read_b128 v[146:149], v185 offset:23136
	ds_read_b128 v[150:153], v185 offset:23168
	ds_read_b128 v[154:157], v185 offset:23200
	ds_read_b128 v[158:161], v185 offset:29696
	ds_read_b128 v[162:165], v185 offset:29728
	ds_read_b128 v[204:207], v185 offset:29760
	ds_read_b128 v[208:211], v185 offset:29792
	ds_read_b128 v[212:215], v185 offset:29824
	ds_read_b128 v[216:219], v185 offset:29856
	s_waitcnt lgkmcnt(11)
	v_mfma_f32_32x32x16_bf16 v[66:81], v[4:7], v[86:89], v[228:243]
	v_add_u32_e32 v4, 0x8800, v187
	s_waitcnt lgkmcnt(5)
	v_mfma_f32_32x32x16_bf16 v[50:65], v[158:161], v[86:89], v[228:243]
	s_cmp_gt_i32 s3, s2
	s_cbranch_scc1 .Lmy_w2_nl
	v_add_u32_e32 v226, 0x3400, v184
	s_waitcnt vmcnt(9)
	ds_write_b128 v201, v[106:109]
	s_waitcnt vmcnt(8)
	ds_write_b128 v202, v[110:113]
	s_waitcnt vmcnt(7)
	ds_write_b128 v203, v[114:117]
	s_waitcnt vmcnt(6)
	ds_write2_b64 v226, v[118:119], v[120:121] offset1:1
	v_add_u32_e32 v226, 0x3400, v186
	s_waitcnt vmcnt(5)
	ds_write2_b64 v226, v[130:131], v[132:133] offset1:1
	s_branch .Lmy_w2_dn

; template <bool ROWRMS>
; __device__ __forceinline__ void gemm_mainloop(const u16* __restrict__ A, int lda, const u16* __restrict__ Bt, int ldb,
;                                               int K, f32x16 (&acc)[2][2], char* smem, float* rs) {
;     ...
; #pragma unroll
;     for (int kh = 0; kh < 2; ++kh) {
;       bf16x8 af[2][2], bfr[2][2];
; #pragma unroll
;       for (int ks = 0; ks < 2; ++ks) {
; #pragma unroll
;         for (int i = 0; i < 2; ++i) af[ks][i] = *(const bf16x8*)(As + aofs + i * 32 * 72 + (kh * 2 + ks) * 16);
; #pragma unroll
;         for (int j = 0; j < 2; ++j) bfr[ks][j] = *(const bf16x8*)(Bs + bofs + j * 32 * 72 + (kh * 2 + ks) * 16);
;       }
; #pragma unroll
;       for (int ks = 0; ks < 2; ++ks)
; #pragma unroll
;         for (int i = 0; i < 2; ++i)
; #pragma unroll
;           for (int j = 0; j < 2; ++j)
;             acc[i][j] = __builtin_amdgcn_mfma_f32_32x32x16_bf16(af[ks][i], bfr[ks][j], acc[i][j], 0, 0, 0);
;     }
.LBB0_1130:
	s_add_i32 s13, s13, 2
	ds_read_b128 v[188:191], v140
	ds_read_b128 v[228:231], v141 offset:18432
	ds_read_b128 v[232:235], v141 offset:23040
	ds_read_b128 v[192:195], v140 offset:4608
	ds_read_b128 v[200:203], v140 offset:32
	ds_read_b128 v[236:239], v141 offset:18464
	ds_read_b128 v[240:243], v141 offset:23072
	ds_read_b128 v[204:207], v140 offset:4640
	s_waitcnt lgkmcnt(6)
	v_mfma_f32_32x32x16_bf16 v[50:65], v[188:191], v[228:231], v[50:65]
	s_waitcnt lgkmcnt(5)
	v_mfma_f32_32x32x16_bf16 v[34:49], v[188:191], v[232:235], v[34:49]
	s_waitcnt lgkmcnt(4)
	v_mfma_f32_32x32x16_bf16 v[18:33], v[192:195], v[228:231], v[18:33]
	v_mfma_f32_32x32x16_bf16 v[2:17], v[192:195], v[232:235], v[2:17]
	ds_read_b128 v[188:191], v140 offset:64
	ds_read_b128 v[228:231], v141 offset:18496
	ds_read_b128 v[232:235], v141 offset:23104
	ds_read_b128 v[192:195], v140 offset:4672
	s_waitcnt lgkmcnt(6)
	v_mfma_f32_32x32x16_bf16 v[50:65], v[200:203], v[236:239], v[50:65]
	s_waitcnt lgkmcnt(5)
	v_mfma_f32_32x32x16_bf16 v[34:49], v[200:203], v[240:243], v[34:49]
	s_waitcnt lgkmcnt(4)
	v_mfma_f32_32x32x16_bf16 v[18:33], v[204:207], v[236:239], v[18:33]
	v_mfma_f32_32x32x16_bf16 v[2:17], v[204:207], v[240:243], v[2:17]
	ds_read_b128 v[200:203], v140 offset:96
	ds_read_b128 v[236:239], v141 offset:18528
	ds_read_b128 v[240:243], v141 offset:23136
	ds_read_b128 v[204:207], v140 offset:4704
	s_waitcnt lgkmcnt(6)
	v_mfma_f32_32x32x16_bf16 v[50:65], v[188:191], v[228:231], v[50:65]
	s_waitcnt lgkmcnt(5)
	v_mfma_f32_32x32x16_bf16 v[34:49], v[188:191], v[232:235], v[34:49]
	s_waitcnt lgkmcnt(4)
	v_mfma_f32_32x32x16_bf16 v[18:33], v[192:195], v[228:231], v[18:33]
	v_mfma_f32_32x32x16_bf16 v[2:17], v[192:195], v[232:235], v[2:17]
	s_waitcnt lgkmcnt(2)
	v_mfma_f32_32x32x16_bf16 v[50:65], v[200:203], v[236:239], v[50:65]
	s_waitcnt lgkmcnt(1)
	v_mfma_f32_32x32x16_bf16 v[34:49], v[200:203], v[240:243], v[34:49]
	s_waitcnt lgkmcnt(0)
	v_mfma_f32_32x32x16_bf16 v[18:33], v[204:207], v[236:239], v[18:33]
	v_mfma_f32_32x32x16_bf16 v[2:17], v[204:207], v[240:243], v[2:17]
	v_lshl_add_u64 v[136:137], v[136:137], 0, s[10:11]
	s_andn2_b64 vcc, exec, s[14:15]
	v_lshl_add_u64 v[138:139], v[138:139], 0, s[10:11]
	s_cbranch_vccz .LBB0_1136

; template <bool ROWRMS>
; __device__ __forceinline__ void gemm_mainloop(const u16* __restrict__ A, int lda, const u16* __restrict__ Bt, int ldb,
;                                               int K, f32x16 (&acc)[2][2], char* smem, float* rs) {
;     ...
;   auto step = [&](GRegs& R, int kt) {
;     __syncthreads();
; #pragma unroll
;     for (int i = 0; i < 4; ++i) {
;       *(u32x4*)(As + wofs + i * 32 * 72) = R.a[i];
;       *(u32x4*)(Bs + wofs + i * 32 * 72) = R.b[i];
;     }
;     if (ROWRMS) {
; #pragma unroll
;       for (int i = 0; i < 4; ++i) {
;         unsigned a[4] = {R.a[i].x, R.a[i].y, R.a[i].z, R.a[i].w};
; #pragma unroll
;         for (int e = 0; e < 4; ++e) {
;           float lo = __uint_as_float(a[e] << 16), hi = __uint_as_float(a[e] & 0xffff0000u);
;           ss[i] += lo * lo + hi * hi;
;         }
;       }
;     }
;     __syncthreads();
;     if (kt + 2 < nk) gl(R, kt + 2);
;     __builtin_amdgcn_sched_barrier(0);
; #pragma unroll
;     for (int kh = 0; kh < 2; ++kh) {
;       bf16x8 af[2][2], bfr[2][2];
; #pragma unroll
;       for (int ks = 0; ks < 2; ++ks) {
; #pragma unroll
;         for (int i = 0; i < 2; ++i) af[ks][i] = *(const bf16x8*)(As + aofs + i * 32 * 72 + (kh * 2 + ks) * 16);
; #pragma unroll
;         for (int j = 0; j < 2; ++j) bfr[ks][j] = *(const bf16x8*)(Bs + bofs + j * 32 * 72 + (kh * 2 + ks) * 16);
;       }
; #pragma unroll
;       for (int ks = 0; ks < 2; ++ks)
; #pragma unroll
;         for (int i = 0; i < 2; ++i)
; #pragma unroll
;           for (int j = 0; j < 2; ++j)
;             acc[i][j] = __builtin_amdgcn_mfma_f32_32x32x16_bf16(af[ks][i], bfr[ks][j], acc[i][j], 0, 0, 0);
;     }
.LBB0_1133:
	ds_read_b128 v[188:191], v140
	ds_read_b128 v[228:231], v141 offset:18432
	ds_read_b128 v[232:235], v141 offset:23040
	ds_read_b128 v[192:195], v140 offset:4608
	ds_read_b128 v[200:203], v140 offset:32
	ds_read_b128 v[236:239], v141 offset:18464
	ds_read_b128 v[240:243], v141 offset:23072
	ds_read_b128 v[204:207], v140 offset:4640
	s_waitcnt lgkmcnt(6)
	v_mfma_f32_32x32x16_bf16 v[50:65], v[188:191], v[228:231], v[50:65]
	s_waitcnt lgkmcnt(5)
	v_mfma_f32_32x32x16_bf16 v[34:49], v[188:191], v[232:235], v[34:49]
	s_waitcnt lgkmcnt(4)
	v_mfma_f32_32x32x16_bf16 v[18:33], v[192:195], v[228:231], v[18:33]
	v_mfma_f32_32x32x16_bf16 v[2:17], v[192:195], v[232:235], v[2:17]
	ds_read_b128 v[188:191], v140 offset:64
	ds_read_b128 v[228:231], v141 offset:18496
	ds_read_b128 v[232:235], v141 offset:23104
	ds_read_b128 v[192:195], v140 offset:4672
	s_waitcnt lgkmcnt(6)
	v_mfma_f32_32x32x16_bf16 v[50:65], v[200:203], v[236:239], v[50:65]
	s_waitcnt lgkmcnt(5)
	v_mfma_f32_32x32x16_bf16 v[34:49], v[200:203], v[240:243], v[34:49]
	s_waitcnt lgkmcnt(4)
	v_mfma_f32_32x32x16_bf16 v[18:33], v[204:207], v[236:239], v[18:33]
	v_mfma_f32_32x32x16_bf16 v[2:17], v[204:207], v[240:243], v[2:17]
	ds_read_b128 v[200:203], v140 offset:96
	ds_read_b128 v[236:239], v141 offset:18528
	ds_read_b128 v[240:243], v141 offset:23136
	ds_read_b128 v[204:207], v140 offset:4704
	s_waitcnt lgkmcnt(6)
	v_mfma_f32_32x32x16_bf16 v[50:65], v[188:191], v[228:231], v[50:65]
	s_waitcnt lgkmcnt(5)
	v_mfma_f32_32x32x16_bf16 v[34:49], v[188:191], v[232:235], v[34:49]
	s_waitcnt lgkmcnt(4)
	v_mfma_f32_32x32x16_bf16 v[18:33], v[192:195], v[228:231], v[18:33]
	v_mfma_f32_32x32x16_bf16 v[2:17], v[192:195], v[232:235], v[2:17]
	s_waitcnt lgkmcnt(2)
	v_mfma_f32_32x32x16_bf16 v[50:65], v[200:203], v[236:239], v[50:65]
	s_waitcnt lgkmcnt(1)
	v_mfma_f32_32x32x16_bf16 v[34:49], v[200:203], v[240:243], v[34:49]
	s_waitcnt lgkmcnt(0)
	v_mfma_f32_32x32x16_bf16 v[18:33], v[204:207], v[236:239], v[18:33]
	v_mfma_f32_32x32x16_bf16 v[2:17], v[204:207], v[240:243], v[2:17]
	s_cmp_gt_u32 s13, 12
	s_barrier
	ds_write_b128 v69, v[78:81]
	ds_write_b128 v69, v[70:73] offset:18432
	ds_write_b128 v69, v[86:89] offset:4608
	ds_write_b128 v69, v[94:97] offset:23040
	ds_write_b128 v69, v[102:105] offset:9216
	ds_write_b128 v69, v[110:113] offset:27648
	ds_write_b128 v69, v[118:121] offset:13824
	ds_write_b128 v69, v[126:129] offset:32256
	s_waitcnt lgkmcnt(0)
	s_barrier
	s_cbranch_scc1 .LBB0_1130
	v_add_co_u32_e32 v86, vcc, 0x10000, v144
	global_load_dwordx4 v[78:81], v[144:145], off offset:384
	global_load_dwordx4 v[70:73], v[142:143], off offset:384
	v_addc_co_u32_e32 v87, vcc, 0, v145, vcc
	v_add_co_u32_e32 v94, vcc, 0x10000, v142
	global_load_dwordx4 v[86:89], v[86:87], off offset:384
	s_nop 0
	v_addc_co_u32_e32 v95, vcc, 0, v143, vcc
	v_add_co_u32_e32 v102, vcc, 0x20000, v144
	global_load_dwordx4 v[94:97], v[94:95], off offset:384
	s_nop 0
	v_addc_co_u32_e32 v103, vcc, 0, v145, vcc
	v_add_co_u32_e32 v110, vcc, 0x20000, v142
	global_load_dwordx4 v[102:105], v[102:103], off offset:384
	s_nop 0
	v_addc_co_u32_e32 v111, vcc, 0, v143, vcc
	v_add_co_u32_e32 v118, vcc, 0x30000, v144
	global_load_dwordx4 v[110:113], v[110:111], off offset:384
	s_nop 0
	v_addc_co_u32_e32 v119, vcc, 0, v145, vcc
	v_add_co_u32_e32 v126, vcc, 0x30000, v142
	global_load_dwordx4 v[118:121], v[118:119], off offset:384
	s_nop 0
	v_addc_co_u32_e32 v127, vcc, 0, v143, vcc
	global_load_dwordx4 v[126:129], v[126:127], off offset:384
	s_branch .LBB0_1130

; __device__ __forceinline__ void gemm_mainloop_256(const u16* __restrict__ A, const u16* __restrict__ Bt,
;                                                   f32x16 (&acc)[4][2], char* smem) {
;     ...
;   for (int kt = 0; kt < 16; ++kt) {
;     __syncthreads();
; #pragma unroll
;     for (int i = 0; i < 8; ++i) *(u32x4*)(As + wofs + i * 32 * 72) = ra[i];
; #pragma unroll
;     for (int i = 0; i < 4; ++i) *(u32x4*)(Bs + wofs + i * 32 * 72) = rb4[i];
;     __syncthreads();
;     if (kt + 1 < 16) gl(kt + 1);
;     __builtin_amdgcn_sched_barrier(0);
; #pragma unroll
;     for (int ks = 0; ks < 4; ++ks) {
;       bf16x8 af[4], bfr[2];
; #pragma unroll
;       for (int i = 0; i < 4; ++i) af[i] = *(const bf16x8*)(As + aofs + i * 32 * 72 + ks * 16);
; #pragma unroll
;       for (int j = 0; j < 2; ++j) bfr[j] = *(const bf16x8*)(Bs + bofs + j * 32 * 72 + ks * 16);
; #pragma unroll
;       for (int i = 0; i < 4; ++i)
; #pragma unroll
;         for (int j = 0; j < 2; ++j)
;           acc[i][j] = __builtin_amdgcn_mfma_f32_32x32x16_bf16(af[i], bfr[j], acc[i][j], 0, 0, 0);
;     }
;     __builtin_amdgcn_sched_barrier(0);
;   }
.LBB0_1254:
	s_waitcnt lgkmcnt(0)
	s_barrier
	v_lshl_add_u64 v[188:189], v[184:185], 0, s[0:1]
	v_lshl_add_u64 v[190:191], v[186:187], 0, s[0:1]
	s_waitcnt vmcnt(0)
	ds_write_b128 v133, v[134:137]
	ds_write_b128 v133, v[138:141] offset:4608
	v_add_co_u32_e32 v192, vcc, s95, v188
	ds_write_b128 v133, v[146:149] offset:9216
	s_nop 0
	v_addc_co_u32_e32 v193, vcc, 0, v189, vcc
	v_add_co_u32_e32 v194, vcc, s17, v188
	ds_write_b128 v133, v[150:153] offset:13824
	s_nop 0
	v_addc_co_u32_e32 v195, vcc, 0, v189, vcc
	v_add_co_u32_e32 v202, vcc, s19, v188
	ds_write_b128 v133, v[154:157] offset:18432
	s_nop 0
	v_addc_co_u32_e32 v203, vcc, 0, v189, vcc
	v_add_co_u32_e32 v204, vcc, s33, v188
	ds_write_b128 v133, v[158:161] offset:23040
	s_nop 0
	v_addc_co_u32_e32 v205, vcc, 0, v189, vcc
	v_add_co_u32_e32 v206, vcc, s37, v188
	ds_write_b128 v133, v[162:165] offset:27648
	s_nop 0
	v_addc_co_u32_e32 v207, vcc, 0, v189, vcc
	v_add_co_u32_e32 v208, vcc, s15, v188
	ds_write_b128 v133, v[166:169] offset:32256
	s_nop 0
	v_addc_co_u32_e32 v209, vcc, 0, v189, vcc
	v_add_co_u32_e32 v210, vcc, s23, v188
	ds_write_b128 v133, v[142:145] offset:36864
	s_nop 0
	v_addc_co_u32_e32 v211, vcc, 0, v189, vcc
	v_add_co_u32_e32 v212, vcc, s95, v190
	ds_write_b128 v133, v[170:173] offset:41472
	s_nop 0
	v_addc_co_u32_e32 v213, vcc, 0, v191, vcc
	v_add_co_u32_e32 v214, vcc, s17, v190
	ds_write_b128 v133, v[174:177] offset:46080
	s_nop 0
	v_addc_co_u32_e32 v215, vcc, 0, v191, vcc
	v_add_co_u32_e32 v216, vcc, s19, v190
	ds_write_b128 v133, v[178:181] offset:50688
	s_nop 0
	v_addc_co_u32_e32 v217, vcc, 0, v191, vcc
	s_waitcnt lgkmcnt(0)
	s_barrier
	global_load_dwordx4 v[134:137], v[188:189], off offset:128
	global_load_dwordx4 v[142:145], v[190:191], off offset:128
	global_load_dwordx4 v[138:141], v[192:193], off offset:128
	global_load_dwordx4 v[146:149], v[194:195], off offset:128
	global_load_dwordx4 v[150:153], v[202:203], off offset:128
	global_load_dwordx4 v[154:157], v[204:205], off offset:128
	global_load_dwordx4 v[158:161], v[206:207], off offset:128
	global_load_dwordx4 v[162:165], v[208:209], off offset:128
	global_load_dwordx4 v[166:169], v[210:211], off offset:128
	global_load_dwordx4 v[170:173], v[212:213], off offset:128
	global_load_dwordx4 v[174:177], v[214:215], off offset:128
	global_load_dwordx4 v[178:181], v[216:217], off offset:128
	ds_read_b128 v[188:191], v182
	ds_read_b128 v[192:195], v130 offset:36864
	ds_read_b128 v[202:205], v130 offset:41472
	ds_read_b128 v[206:209], v182 offset:4608
	ds_read_b128 v[210:213], v182 offset:9216
	ds_read_b128 v[214:217], v182 offset:13824
	s_waitcnt lgkmcnt(4)
	v_mfma_f32_32x32x16_bf16 v[114:129], v[188:191], v[192:195], v[114:129]
	s_waitcnt lgkmcnt(3)
	v_mfma_f32_32x32x16_bf16 v[98:113], v[188:191], v[202:205], v[98:113]
	ds_read_b128 v[188:191], v182 offset:32
	ds_read_b128 v[218:221], v130 offset:36896
	ds_read_b128 v[222:225], v130 offset:41504
	s_waitcnt lgkmcnt(5)
	v_mfma_f32_32x32x16_bf16 v[82:97], v[206:209], v[192:195], v[82:97]
	v_mfma_f32_32x32x16_bf16 v[66:81], v[206:209], v[202:205], v[66:81]
	ds_read_b128 v[206:209], v182 offset:4640
	s_waitcnt lgkmcnt(5)
	v_mfma_f32_32x32x16_bf16 v[50:65], v[210:213], v[192:195], v[50:65]
	v_mfma_f32_32x32x16_bf16 v[34:49], v[210:213], v[202:205], v[34:49]
	ds_read_b128 v[210:213], v182 offset:9248
	s_waitcnt lgkmcnt(5)
	v_mfma_f32_32x32x16_bf16 v[18:33], v[214:217], v[192:195], v[18:33]
	v_mfma_f32_32x32x16_bf16 v[2:17], v[214:217], v[202:205], v[2:17]
	ds_read_b128 v[214:217], v182 offset:13856
	s_waitcnt lgkmcnt(4)
	v_mfma_f32_32x32x16_bf16 v[114:129], v[188:191], v[218:221], v[114:129]
	s_waitcnt lgkmcnt(3)
	v_mfma_f32_32x32x16_bf16 v[98:113], v[188:191], v[222:225], v[98:113]
	ds_read_b128 v[188:191], v182 offset:64
	ds_read_b128 v[192:195], v130 offset:36928
	ds_read_b128 v[202:205], v130 offset:41536
	s_waitcnt lgkmcnt(5)
	v_mfma_f32_32x32x16_bf16 v[82:97], v[206:209], v[218:221], v[82:97]
	v_mfma_f32_32x32x16_bf16 v[66:81], v[206:209], v[222:225], v[66:81]
	ds_read_b128 v[206:209], v182 offset:4672
	s_waitcnt lgkmcnt(5)
	v_mfma_f32_32x32x16_bf16 v[50:65], v[210:213], v[218:221], v[50:65]
	v_mfma_f32_32x32x16_bf16 v[34:49], v[210:213], v[222:225], v[34:49]
	ds_read_b128 v[210:213], v182 offset:9280
	s_waitcnt lgkmcnt(5)
	v_mfma_f32_32x32x16_bf16 v[18:33], v[214:217], v[218:221], v[18:33]
	v_mfma_f32_32x32x16_bf16 v[2:17], v[214:217], v[222:225], v[2:17]
	ds_read_b128 v[214:217], v182 offset:13888
	s_waitcnt lgkmcnt(4)
	v_mfma_f32_32x32x16_bf16 v[114:129], v[188:191], v[192:195], v[114:129]
	s_waitcnt lgkmcnt(3)
	v_mfma_f32_32x32x16_bf16 v[98:113], v[188:191], v[202:205], v[98:113]
	ds_read_b128 v[188:191], v182 offset:96
	ds_read_b128 v[218:221], v130 offset:36960
	ds_read_b128 v[222:225], v130 offset:41568
	s_waitcnt lgkmcnt(5)
	v_mfma_f32_32x32x16_bf16 v[82:97], v[206:209], v[192:195], v[82:97]
	v_mfma_f32_32x32x16_bf16 v[66:81], v[206:209], v[202:205], v[66:81]
	ds_read_b128 v[206:209], v182 offset:4704
	s_waitcnt lgkmcnt(5)
	v_mfma_f32_32x32x16_bf16 v[50:65], v[210:213], v[192:195], v[50:65]
	v_mfma_f32_32x32x16_bf16 v[34:49], v[210:213], v[202:205], v[34:49]
	ds_read_b128 v[210:213], v182 offset:9312
	s_waitcnt lgkmcnt(5)
	v_mfma_f32_32x32x16_bf16 v[18:33], v[214:217], v[192:195], v[18:33]
	v_mfma_f32_32x32x16_bf16 v[2:17], v[214:217], v[202:205], v[2:17]
	ds_read_b128 v[214:217], v182 offset:13920
	s_waitcnt lgkmcnt(4)
	v_mfma_f32_32x32x16_bf16 v[114:129], v[188:191], v[218:221], v[114:129]
	s_waitcnt lgkmcnt(3)
	v_mfma_f32_32x32x16_bf16 v[98:113], v[188:191], v[222:225], v[98:113]
	s_waitcnt lgkmcnt(2)
	v_mfma_f32_32x32x16_bf16 v[82:97], v[206:209], v[218:221], v[82:97]
	v_mfma_f32_32x32x16_bf16 v[66:81], v[206:209], v[222:225], v[66:81]
	s_waitcnt lgkmcnt(1)
	v_mfma_f32_32x32x16_bf16 v[50:65], v[210:213], v[218:221], v[50:65]
	v_mfma_f32_32x32x16_bf16 v[34:49], v[210:213], v[222:225], v[34:49]
	s_waitcnt lgkmcnt(0)
	v_mfma_f32_32x32x16_bf16 v[18:33], v[214:217], v[218:221], v[18:33]
	v_mfma_f32_32x32x16_bf16 v[2:17], v[214:217], v[222:225], v[2:17]
	s_add_u32 s0, s0, 0x80
	s_addc_u32 s1, s1, 0
	s_cmpk_lg_i32 s0, 0x780
	s_cbranch_scc1 .LBB0_1254
; __device__ __forceinline__ void gemm_mainloop_256(const u16* __restrict__ A, const u16* __restrict__ Bt,
;                                                   f32x16 (&acc)[4][2], char* smem) {
;     ...
;     __syncthreads();
; #pragma unroll
;     for (int i = 0; i < 8; ++i) *(u32x4*)(As + wofs + i * 32 * 72) = ra[i];
; #pragma unroll
;     for (int i = 0; i < 4; ++i) *(u32x4*)(Bs + wofs + i * 32 * 72) = rb4[i];
;     __syncthreads();
;     if (kt + 1 < 16) gl(kt + 1);
;     __builtin_amdgcn_sched_barrier(0);
; #pragma unroll
;     for (int ks = 0; ks < 4; ++ks) {
;       bf16x8 af[4], bfr[2];
; #pragma unroll
;       for (int i = 0; i < 4; ++i) af[i] = *(const bf16x8*)(As + aofs + i * 32 * 72 + ks * 16);
; #pragma unroll
;       for (int j = 0; j < 2; ++j) bfr[j] = *(const bf16x8*)(Bs + bofs + j * 32 * 72 + ks * 16);
; #pragma unroll
;       for (int i = 0; i < 4; ++i)
; #pragma unroll
;         for (int j = 0; j < 2; ++j)
;           acc[i][j] = __builtin_amdgcn_mfma_f32_32x32x16_bf16(af[i], bfr[j], acc[i][j], 0, 0, 0);
;     }
;     __builtin_amdgcn_sched_barrier(0);
;   }
;   __syncthreads();
	s_barrier
	s_waitcnt vmcnt(10)
	ds_write_b128 v133, v[134:137]
	s_waitcnt vmcnt(9)
	ds_write_b128 v133, v[138:141] offset:4608
	s_waitcnt vmcnt(8)
	ds_write_b128 v133, v[146:149] offset:9216
	s_waitcnt vmcnt(7)
	ds_write_b128 v133, v[150:153] offset:13824
	s_waitcnt vmcnt(6)
	ds_write_b128 v133, v[154:157] offset:18432
	s_waitcnt vmcnt(5)
	ds_write_b128 v133, v[158:161] offset:23040
	s_waitcnt vmcnt(4)
	ds_write_b128 v133, v[162:165] offset:27648
	s_waitcnt vmcnt(3)
	ds_write_b128 v133, v[166:169] offset:32256
	ds_write_b128 v133, v[142:145] offset:36864
	s_waitcnt vmcnt(2)
	ds_write_b128 v133, v[170:173] offset:41472
	s_waitcnt vmcnt(1)
	ds_write_b128 v133, v[174:177] offset:46080
	s_waitcnt vmcnt(0)
	ds_write_b128 v133, v[178:181] offset:50688
	s_waitcnt lgkmcnt(0)
	s_barrier
	ds_read_b128 v[134:137], v182
	ds_read_b128 v[138:141], v130 offset:36864
	ds_read_b128 v[142:145], v130 offset:41472
	ds_read_b128 v[206:209], v182 offset:4608
	ds_read_b128 v[210:213], v182 offset:9216
	ds_read_b128 v[214:217], v182 offset:13824
	s_waitcnt lgkmcnt(4)
	v_mfma_f32_32x32x16_bf16 v[114:129], v[134:137], v[138:141], v[114:129]
	s_waitcnt lgkmcnt(3)
	v_mfma_f32_32x32x16_bf16 v[98:113], v[134:137], v[142:145], v[98:113]
	ds_read_b128 v[134:137], v182 offset:32
	ds_read_b128 v[218:221], v130 offset:36896
	ds_read_b128 v[222:225], v130 offset:41504
	s_waitcnt lgkmcnt(5)
	v_mfma_f32_32x32x16_bf16 v[82:97], v[206:209], v[138:141], v[82:97]
	v_mfma_f32_32x32x16_bf16 v[66:81], v[206:209], v[142:145], v[66:81]
	ds_read_b128 v[206:209], v182 offset:4640
	s_waitcnt lgkmcnt(5)
	v_mfma_f32_32x32x16_bf16 v[50:65], v[210:213], v[138:141], v[50:65]
	v_mfma_f32_32x32x16_bf16 v[34:49], v[210:213], v[142:145], v[34:49]
	ds_read_b128 v[210:213], v182 offset:9248
	s_waitcnt lgkmcnt(5)
	v_mfma_f32_32x32x16_bf16 v[18:33], v[214:217], v[138:141], v[18:33]
	v_mfma_f32_32x32x16_bf16 v[2:17], v[214:217], v[142:145], v[2:17]
	ds_read_b128 v[214:217], v182 offset:13856
	s_waitcnt lgkmcnt(4)
	v_mfma_f32_32x32x16_bf16 v[114:129], v[134:137], v[218:221], v[114:129]
	s_waitcnt lgkmcnt(3)
	v_mfma_f32_32x32x16_bf16 v[98:113], v[134:137], v[222:225], v[98:113]
	ds_read_b128 v[134:137], v182 offset:64
	ds_read_b128 v[138:141], v130 offset:36928
	ds_read_b128 v[142:145], v130 offset:41536
	s_waitcnt lgkmcnt(5)
	v_mfma_f32_32x32x16_bf16 v[82:97], v[206:209], v[218:221], v[82:97]
	v_mfma_f32_32x32x16_bf16 v[66:81], v[206:209], v[222:225], v[66:81]
	ds_read_b128 v[206:209], v182 offset:4672
	s_waitcnt lgkmcnt(5)
	v_mfma_f32_32x32x16_bf16 v[50:65], v[210:213], v[218:221], v[50:65]
	v_mfma_f32_32x32x16_bf16 v[34:49], v[210:213], v[222:225], v[34:49]
	ds_read_b128 v[210:213], v182 offset:9280
	s_waitcnt lgkmcnt(5)
	v_mfma_f32_32x32x16_bf16 v[18:33], v[214:217], v[218:221], v[18:33]
	v_mfma_f32_32x32x16_bf16 v[2:17], v[214:217], v[222:225], v[2:17]
	ds_read_b128 v[214:217], v182 offset:13888
	s_waitcnt lgkmcnt(4)
	v_mfma_f32_32x32x16_bf16 v[114:129], v[134:137], v[138:141], v[114:129]
	s_waitcnt lgkmcnt(3)
	v_mfma_f32_32x32x16_bf16 v[98:113], v[134:137], v[142:145], v[98:113]
	ds_read_b128 v[134:137], v182 offset:96
	ds_read_b128 v[218:221], v130 offset:36960
	ds_read_b128 v[222:225], v130 offset:41568
	s_waitcnt lgkmcnt(5)
	v_mfma_f32_32x32x16_bf16 v[82:97], v[206:209], v[138:141], v[82:97]
	v_mfma_f32_32x32x16_bf16 v[66:81], v[206:209], v[142:145], v[66:81]
	ds_read_b128 v[206:209], v182 offset:4704
	s_waitcnt lgkmcnt(5)
	v_mfma_f32_32x32x16_bf16 v[50:65], v[210:213], v[138:141], v[50:65]
	v_mfma_f32_32x32x16_bf16 v[34:49], v[210:213], v[142:145], v[34:49]
	ds_read_b128 v[210:213], v182 offset:9312
	s_waitcnt lgkmcnt(5)
	v_mfma_f32_32x32x16_bf16 v[18:33], v[214:217], v[138:141], v[18:33]
	v_mfma_f32_32x32x16_bf16 v[2:17], v[214:217], v[142:145], v[2:17]
	ds_read_b128 v[214:217], v182 offset:13920
	s_waitcnt lgkmcnt(4)
	v_mfma_f32_32x32x16_bf16 v[114:129], v[134:137], v[218:221], v[114:129]
	s_waitcnt lgkmcnt(3)
	v_mfma_f32_32x32x16_bf16 v[98:113], v[134:137], v[222:225], v[98:113]
	s_waitcnt lgkmcnt(2)
	v_mfma_f32_32x32x16_bf16 v[82:97], v[206:209], v[218:221], v[82:97]
	v_mfma_f32_32x32x16_bf16 v[66:81], v[206:209], v[222:225], v[66:81]
	s_waitcnt lgkmcnt(1)
	v_mfma_f32_32x32x16_bf16 v[50:65], v[210:213], v[218:221], v[50:65]
	v_mfma_f32_32x32x16_bf16 v[34:49], v[210:213], v[222:225], v[34:49]
	s_waitcnt lgkmcnt(0)
	v_mfma_f32_32x32x16_bf16 v[18:33], v[214:217], v[218:221], v[18:33]
	v_mfma_f32_32x32x16_bf16 v[2:17], v[214:217], v[222:225], v[2:17]
	v_mov_b32_e32 v130, v198
	s_barrier
; template <int Q>
; __device__ __forceinline__ void stage_c4(const f32x16 (&acc)[4][2], float* Cs) {
;   const int tid = tid_opaque(), lane = tid & 63, w = tid >> 6, wm = w >> 1, wn = w & 1;
;   if (wm == (Q >> 1)) {
; #pragma unroll
;     for (int ii = 0; ii < 2; ++ii)
; #pragma unroll
;       for (int j = 0; j < 2; ++j)
; #pragma unroll
;         for (int r = 0; r < 16; ++r) {
;           int row = ii * 32 + (r & 3) + 8 * (r >> 2) + 4 * (lane >> 5);
;           int col = wn * 64 + j * 32 + (lane & 31);
;           Cs[row * 132 + col] = acc[2 * (Q & 1) + ii][j][r];
;         }
;   }
; }
	s_nop 0
	v_cmp_gt_u32_e32 vcc, s14, v130
	s_and_saveexec_b64 s[0:1], vcc
	s_cbranch_execz .LBB0_1257
	v_lshrrev_b32_e32 v133, 3, v130
	v_lshlrev_b32_e32 v130, 2, v130
	v_and_b32_e32 v134, 4, v133
	v_and_b32_e32 v135, 0x17c, v130
	v_mad_u32_u24 v136, v134, s18, v135
	v_add_u32_e32 v137, 0x400, v136
	ds_write2_b32 v137, v116, v117 offset0:8 offset1:140
	v_add_u32_e32 v137, 0x1000, v136
	ds_write2_b32 v136, v114, v115 offset1:132
	ds_write2_b32 v137, v118, v119 offset0:32 offset1:164
	ds_write_b32 v136, v120 offset:5280
	v_or_b32_e32 v137, 11, v133
	v_mul_lo_u32 v137, v137, s18
	v_add_u32_e32 v138, v137, v135
	ds_write_b32 v138, v121
	v_add_u32_e32 v138, 0x2000, v136
	ds_write2_b32 v138, v122, v123 offset0:64 offset1:196
	v_add_u32_e32 v138, 0x2400, v136
	ds_write2_b32 v138, v124, v125 offset0:72 offset1:204
	v_add_u32_e32 v138, 0x3000, v136
	ds_write2_b32 v138, v126, v127 offset0:96 offset1:228
	ds_write_b32 v136, v128 offset:13728
	v_or_b32_e32 v138, 27, v133
	v_mul_lo_u32 v138, v138, s18
	v_or_b32_e32 v130, 0x80, v130
	v_add_u32_e32 v139, v138, v135
	v_mad_u32_u24 v134, v134, s18, v130
	ds_write_b32 v139, v129
	v_add_u32_e32 v139, 0x400, v134
	ds_write2_b32 v139, v100, v101 offset0:8 offset1:140
	v_add_u32_e32 v139, 0x1000, v134
	v_add_u32_e32 v137, v137, v130
	ds_write2_b32 v134, v98, v99 offset1:132
	ds_write2_b32 v139, v102, v103 offset0:32 offset1:164
	ds_write_b32 v134, v104 offset:5280
	ds_write_b32 v137, v105
	v_add_u32_e32 v137, 0x2000, v134
	ds_write2_b32 v137, v106, v107 offset0:64 offset1:196
	v_add_u32_e32 v137, 0x2400, v134
	ds_write2_b32 v137, v108, v109 offset0:72 offset1:204
	v_add_u32_e32 v137, 0x3000, v134
	ds_write2_b32 v137, v110, v111 offset0:96 offset1:228
	ds_write_b32 v134, v112 offset:13728
	v_add_u32_e32 v137, v138, v130
	ds_write_b32 v137, v113
	v_add_u32_e32 v137, 0x4200, v136
	ds_write2_b32 v137, v82, v83 offset1:132
	v_add_u32_e32 v137, 0x4600, v136
	ds_write2_b32 v137, v84, v85 offset0:8 offset1:140
	v_add_u32_e32 v137, 0x5200, v136
	ds_write2_b32 v137, v86, v87 offset0:32 offset1:164
	ds_write_b32 v136, v88 offset:22176
	v_or_b32_e32 v137, 43, v133
	v_mul_lo_u32 v137, v137, s18
	v_add_u32_e32 v138, v137, v135
	ds_write_b32 v138, v89
	v_add_u32_e32 v138, 0x6200, v136
	v_or_b32_e32 v133, 59, v133
	ds_write2_b32 v138, v90, v91 offset0:64 offset1:196
	v_add_u32_e32 v138, 0x6600, v136
	v_mul_lo_u32 v133, v133, s18
	ds_write2_b32 v138, v92, v93 offset0:72 offset1:204
	v_add_u32_e32 v138, 0x7200, v136
	v_add_u32_e32 v135, v133, v135
	ds_write2_b32 v138, v94, v95 offset0:96 offset1:228
	ds_write_b32 v136, v96 offset:30624
	ds_write_b32 v135, v97
	v_add_u32_e32 v135, 0x4200, v134
	ds_write2_b32 v135, v66, v67 offset1:132
	v_add_u32_e32 v135, 0x4600, v134
	ds_write2_b32 v135, v68, v69 offset0:8 offset1:140
	v_add_u32_e32 v135, 0x5200, v134
	ds_write2_b32 v135, v70, v71 offset0:32 offset1:164
	ds_write_b32 v134, v72 offset:22176
	v_add_u32_e32 v135, v137, v130
	ds_write_b32 v135, v73
	v_add_u32_e32 v135, 0x6200, v134
	ds_write2_b32 v135, v74, v75 offset0:64 offset1:196
	v_add_u32_e32 v135, 0x6600, v134
	ds_write2_b32 v135, v76, v77 offset0:72 offset1:204
	v_add_u32_e32 v135, 0x7200, v134
	v_add_u32_e32 v130, v133, v130
	ds_write2_b32 v135, v78, v79 offset0:96 offset1:228
	ds_write_b32 v134, v80 offset:30624
	ds_write_b32 v130, v81

; template <bool ROWRMS>
; __device__ __forceinline__ void gemm_mainloop(const u16* __restrict__ A, int lda, const u16* __restrict__ Bt, int ldb,
;                                               int K, f32x16 (&acc)[2][2], char* smem, float* rs) {
;     ...
;   auto step = [&](GRegs& R, int kt) {
;     __syncthreads();
; #pragma unroll
;     for (int i = 0; i < 4; ++i) {
;       *(u32x4*)(As + wofs + i * 32 * 72) = R.a[i];
;       *(u32x4*)(Bs + wofs + i * 32 * 72) = R.b[i];
;     }
;     if (ROWRMS) {
; #pragma unroll
;       for (int i = 0; i < 4; ++i) {
;         unsigned a[4] = {R.a[i].x, R.a[i].y, R.a[i].z, R.a[i].w};
; #pragma unroll
;         for (int e = 0; e < 4; ++e) {
;           float lo = __uint_as_float(a[e] << 16), hi = __uint_as_float(a[e] & 0xffff0000u);
;           ss[i] += lo * lo + hi * hi;
;         }
;       }
;     }
;     __syncthreads();
;     if (kt + 2 < nk) gl(R, kt + 2);
;     __builtin_amdgcn_sched_barrier(0);
; #pragma unroll
;     for (int kh = 0; kh < 2; ++kh) {
;       bf16x8 af[2][2], bfr[2][2];
; #pragma unroll
;       for (int ks = 0; ks < 2; ++ks) {
; #pragma unroll
;         for (int i = 0; i < 2; ++i) af[ks][i] = *(const bf16x8*)(As + aofs + i * 32 * 72 + (kh * 2 + ks) * 16);
; #pragma unroll
;         for (int j = 0; j < 2; ++j) bfr[ks][j] = *(const bf16x8*)(Bs + bofs + j * 32 * 72 + (kh * 2 + ks) * 16);
;       }
; #pragma unroll
;       for (int ks = 0; ks < 2; ++ks)
; #pragma unroll
;         for (int i = 0; i < 2; ++i)
; #pragma unroll
;           for (int j = 0; j < 2; ++j)
;             acc[i][j] = __builtin_amdgcn_mfma_f32_32x32x16_bf16(af[ks][i], bfr[ks][j], acc[i][j], 0, 0, 0);
;     }
.LBB0_1801:
	ds_read_b128 v[188:191], v142
	ds_read_b128 v[228:231], v143 offset:18432
	ds_read_b128 v[232:235], v143 offset:23040
	ds_read_b128 v[192:195], v142 offset:4608
	ds_read_b128 v[200:203], v142 offset:32
	ds_read_b128 v[236:239], v143 offset:18464
	ds_read_b128 v[240:243], v143 offset:23072
	ds_read_b128 v[204:207], v142 offset:4640
	s_waitcnt lgkmcnt(6)
	v_mfma_f32_32x32x16_bf16 v[50:65], v[188:191], v[228:231], v[50:65]
	s_waitcnt lgkmcnt(5)
	v_mfma_f32_32x32x16_bf16 v[34:49], v[188:191], v[232:235], v[34:49]
	s_waitcnt lgkmcnt(4)
	v_mfma_f32_32x32x16_bf16 v[18:33], v[192:195], v[228:231], v[18:33]
	v_mfma_f32_32x32x16_bf16 v[2:17], v[192:195], v[232:235], v[2:17]
	ds_read_b128 v[188:191], v142 offset:64
	ds_read_b128 v[228:231], v143 offset:18496
	ds_read_b128 v[232:235], v143 offset:23104
	ds_read_b128 v[192:195], v142 offset:4672
	s_waitcnt lgkmcnt(6)
	v_mfma_f32_32x32x16_bf16 v[50:65], v[200:203], v[236:239], v[50:65]
	s_waitcnt lgkmcnt(5)
	v_mfma_f32_32x32x16_bf16 v[34:49], v[200:203], v[240:243], v[34:49]
	s_waitcnt lgkmcnt(4)
	v_mfma_f32_32x32x16_bf16 v[18:33], v[204:207], v[236:239], v[18:33]
	v_mfma_f32_32x32x16_bf16 v[2:17], v[204:207], v[240:243], v[2:17]
	ds_read_b128 v[200:203], v142 offset:96
	ds_read_b128 v[236:239], v143 offset:18528
	ds_read_b128 v[240:243], v143 offset:23136
	ds_read_b128 v[204:207], v142 offset:4704
	s_waitcnt lgkmcnt(6)
	v_mfma_f32_32x32x16_bf16 v[50:65], v[188:191], v[228:231], v[50:65]
	s_waitcnt lgkmcnt(5)
	v_mfma_f32_32x32x16_bf16 v[34:49], v[188:191], v[232:235], v[34:49]
	s_waitcnt lgkmcnt(4)
	v_mfma_f32_32x32x16_bf16 v[18:33], v[192:195], v[228:231], v[18:33]
	v_mfma_f32_32x32x16_bf16 v[2:17], v[192:195], v[232:235], v[2:17]
	s_waitcnt lgkmcnt(2)
	v_mfma_f32_32x32x16_bf16 v[50:65], v[200:203], v[236:239], v[50:65]
	s_waitcnt lgkmcnt(1)
	v_mfma_f32_32x32x16_bf16 v[34:49], v[200:203], v[240:243], v[34:49]
	s_waitcnt lgkmcnt(0)
	v_mfma_f32_32x32x16_bf16 v[18:33], v[204:207], v[236:239], v[18:33]
	v_mfma_f32_32x32x16_bf16 v[2:17], v[204:207], v[240:243], v[2:17]
	s_cmp_gt_u32 s19, 12
	s_barrier
	ds_write_b128 v137, v[66:69]
	ds_write_b128 v137, v[70:73] offset:18432
	ds_write_b128 v137, v[78:81] offset:4608
	ds_write_b128 v137, v[98:101] offset:23040
	ds_write_b128 v137, v[74:77] offset:9216
	ds_write_b128 v137, v[110:113] offset:27648
	ds_write_b128 v137, v[82:85] offset:13824
	ds_write_b128 v137, v[86:89] offset:32256
	s_waitcnt lgkmcnt(0)
	s_barrier
	s_cbranch_scc1 .LBB0_1798
	v_add_co_u32_e32 v66, vcc, 0xe4701000, v146
	s_nop 1
	v_addc_co_u32_e32 v67, vcc, -1, v147, vcc
	v_add_co_u32_e32 v70, vcc, 0x100000, v144
	global_load_dwordx4 v[66:69], v[66:67], off offset:-3712
	s_nop 0
	v_addc_co_u32_e32 v71, vcc, 0, v145, vcc
	v_add_co_u32_e32 v74, vcc, 0xe4711000, v146
	global_load_dwordx4 v[70:73], v[70:71], off offset:384
	s_nop 0
	v_addc_co_u32_e32 v75, vcc, -1, v147, vcc
	global_load_dwordx4 v[78:81], v[74:75], off offset:-3712
	v_add_co_u32_e32 v74, vcc, 0x110000, v144
	s_nop 1
	v_addc_co_u32_e32 v75, vcc, 0, v145, vcc
	global_load_dwordx4 v[98:101], v[74:75], off offset:384
	v_add_co_u32_e32 v74, vcc, 0xe4721000, v146
	s_nop 1
	v_addc_co_u32_e32 v75, vcc, -1, v147, vcc
	v_add_co_u32_e32 v82, vcc, 0x120000, v144
	global_load_dwordx4 v[74:77], v[74:75], off offset:-3712
	s_nop 0
	v_addc_co_u32_e32 v83, vcc, 0, v145, vcc
	global_load_dwordx4 v[110:113], v[82:83], off offset:384
	v_add_co_u32_e32 v82, vcc, 0xe4731000, v146
	s_nop 1
	v_addc_co_u32_e32 v83, vcc, -1, v147, vcc
	v_add_co_u32_e32 v86, vcc, 0x130000, v144
	global_load_dwordx4 v[82:85], v[82:83], off offset:-3712
	s_nop 0
	v_addc_co_u32_e32 v87, vcc, 0, v145, vcc
	global_load_dwordx4 v[86:89], v[86:87], off offset:384
	s_branch .LBB0_1798

; template <int DQK, int MODE> ...
;     ...
;         float rsum = 0.f;
; #pragma unroll
;         for (int ku = 0; ku < 2; ++ku)
; #pragma unroll
;           for (int r = 0; r < 16; ++r) {
;             float e = __builtin_amdgcn_exp2f(S[ku][r]);
;             S[ku][r] = e;
;             rsum += e;
;           }
;         lsum += rsum;
;     ...
; #pragma unroll
;       for (int s = 0; s < 4; ++s) {
;         const int ku = s >> 1, b = 8 * (s & 1);
;         u32x4 t;
;         t.x = pack2(S[ku][b + 0], S[ku][b + 1]);
;         t.y = pack2(S[ku][b + 2], S[ku][b + 3]);
;         t.z = pack2(S[ku][b + 4], S[ku][b + 5]);
;         t.w = pack2(S[ku][b + 6], S[ku][b + 7]);
;         pf[s] = __builtin_bit_cast(bf16x8, t);
;       }
;       if (MODE == 2) {
; #pragma unroll
;         for (int du = 0; du < 2; ++du)
; #pragma unroll
;           for (int s4 = 0; s4 < 4; ++s4) {
;             const u16* vp = Vs + (du * 32 + ql) * VST + 16 * s4 + 4 * hh;
;             u32x2 a = *(const u32x2*)vp;
;             u32x2 b = *(const u32x2*)(vp + 8);
;             vf[du][s4] = (u32x4){a.x, a.y, b.x, b.y};
;           }
;       }
; #pragma unroll
;       for (int s4 = 0; s4 < 4; ++s4)
; #pragma unroll
;         for (int du = 0; du < 2; ++du)
;           O[du] = __builtin_amdgcn_mfma_f32_32x32x16_bf16(__builtin_bit_cast(bf16x8, vf[du][s4]), pf[s4], O[du], 0, 0, 0);
.LBB0_2124:
	s_setprio 1
	v_exp_f32_e32 v14, v64
	v_exp_f32_e32 v64, v65
	v_exp_f32_e32 v65, v66
	v_exp_f32_e32 v66, v67
	v_add_f32_e32 v15, 0, v14
	v_exp_f32_e32 v67, v68
	v_add_f32_e32 v15, v64, v15
	v_exp_f32_e32 v68, v69
	v_add_f32_e32 v15, v65, v15
	v_exp_f32_e32 v69, v70
	v_add_f32_e32 v15, v66, v15
	v_exp_f32_e32 v70, v71
	v_add_f32_e32 v15, v67, v15
	v_exp_f32_e32 v71, v72
	v_add_f32_e32 v15, v68, v15
	v_exp_f32_e32 v72, v73
	v_add_f32_e32 v15, v69, v15
	v_exp_f32_e32 v73, v74
	v_add_f32_e32 v15, v70, v15
	v_exp_f32_e32 v74, v75
	v_exp_f32_e32 v75, v76
	v_exp_f32_e32 v76, v77
	v_exp_f32_e32 v77, v78
	v_exp_f32_e32 v78, v79
	v_exp_f32_e32 v79, v48
	v_exp_f32_e32 v203, v49
	v_exp_f32_e32 v204, v50
	v_exp_f32_e32 v205, v51
	v_cvt_pk_bf16_f32 v48, v14, v64
	v_cvt_pk_bf16_f32 v49, v65, v66
	v_cvt_pk_bf16_f32 v50, v67, v68
	v_cvt_pk_bf16_f32 v51, v69, v70
	v_add_f32_e32 v15, v71, v15
	v_add_f32_e32 v15, v72, v15
	s_waitcnt lgkmcnt(7)
	v_mfma_f32_32x32x16_bf16 v[32:47], v[160:163], v[48:51], v[32:47]
	v_add_f32_e32 v15, v73, v15
	v_add_f32_e32 v15, v74, v15
	v_add_f32_e32 v15, v75, v15
	v_add_f32_e32 v15, v76, v15
	v_add_f32_e32 v15, v77, v15
	v_add_f32_e32 v15, v78, v15
	v_exp_f32_e32 v206, v52
	s_waitcnt lgkmcnt(3)
	v_mfma_f32_32x32x16_bf16 v[16:31], v[156:159], v[48:51], v[16:31]
	v_exp_f32_e32 v207, v53
	v_exp_f32_e32 v208, v54
	v_exp_f32_e32 v209, v55
	v_cvt_pk_bf16_f32 v52, v71, v72
	v_cvt_pk_bf16_f32 v53, v73, v74
	v_cvt_pk_bf16_f32 v54, v75, v76
	v_cvt_pk_bf16_f32 v55, v77, v78
	v_add_f32_e32 v15, v79, v15
	v_add_f32_e32 v15, v203, v15
	v_mfma_f32_32x32x16_bf16 v[32:47], v[152:155], v[52:55], v[32:47]
	v_add_f32_e32 v15, v204, v15
	v_add_f32_e32 v15, v205, v15
	v_add_f32_e32 v15, v206, v15
	v_exp_f32_e32 v210, v56
	v_add_f32_e32 v15, v207, v15
	v_exp_f32_e32 v211, v57
	v_add_f32_e32 v15, v208, v15
	s_waitcnt lgkmcnt(2)
	v_mfma_f32_32x32x16_bf16 v[16:31], v[148:151], v[52:55], v[16:31]
	v_exp_f32_e32 v212, v58
	v_add_f32_e32 v15, v209, v15
	v_exp_f32_e32 v213, v59
	v_cvt_pk_bf16_f32 v56, v79, v203
	v_cvt_pk_bf16_f32 v57, v204, v205
	v_cvt_pk_bf16_f32 v58, v206, v207
	v_cvt_pk_bf16_f32 v59, v208, v209
	v_add_f32_e32 v15, v210, v15
	v_exp_f32_e32 v214, v60
	v_mfma_f32_32x32x16_bf16 v[32:47], v[144:147], v[56:59], v[32:47]
	v_add_f32_e32 v15, v211, v15
	v_exp_f32_e32 v215, v61
	v_add_f32_e32 v15, v212, v15
	v_exp_f32_e32 v216, v62
	v_add_f32_e32 v15, v213, v15
	v_exp_f32_e32 v63, v63
	v_add_f32_e32 v15, v214, v15
	s_waitcnt lgkmcnt(1)
	v_mfma_f32_32x32x16_bf16 v[16:31], v[10:13], v[56:59], v[16:31]
	v_add_f32_e32 v15, v215, v15
	v_add_f32_e32 v15, v216, v15
	v_add_f32_e32 v15, v63, v15
	v_cvt_pk_bf16_f32 v60, v210, v211
	v_cvt_pk_bf16_f32 v61, v212, v213
	v_cvt_pk_bf16_f32 v62, v214, v215
	v_cvt_pk_bf16_f32 v63, v216, v63
	v_add_f32_e32 v175, v175, v15
	s_andn2_b64 s[10:11], s[10:11], exec
	v_mfma_f32_32x32x16_bf16 v[32:47], v[6:9], v[60:63], v[32:47]
	s_waitcnt lgkmcnt(0)
	v_mfma_f32_32x32x16_bf16 v[16:31], v[2:5], v[60:63], v[16:31]
	s_setprio 0

; template <int DQK, int MODE> ...
;     ...
;       {
;         bf16x8 kf[2][NKK];
; #pragma unroll
;         for (int ku = 0; ku < 2; ++ku)
; #pragma unroll
;           for (int kk = 0; kk < NKK; ++kk)
;             kf[ku][kk] = *(const bf16x8*)(Ks + (ku * 32 + ql) * KST + kk * 16 + hh * 8);
;         __builtin_amdgcn_sched_barrier(0);
; #pragma unroll
;         for (int ku = 0; ku < 2; ++ku)
; #pragma unroll
;           for (int r = 0; r < 16; ++r) S[ku][r] = cinit;
; #pragma unroll
;         for (int kk = 0; kk < NKK; ++kk)
; #pragma unroll
;           for (int ku = 0; ku < 2; ++ku)
;             S[ku] = __builtin_amdgcn_mfma_f32_32x32x16_bf16(kf[ku][kk], qf[kk], S[ku], 0, 0, 0);
;       }
.LBB0_2129:
	s_and_saveexec_b64 s[14:15], s[30:31]
	s_cbranch_execz .Lmy_ia0_b
	ds_read_b128 v[2:5], v183
	ds_read_b128 v[6:9], v183 offset:32
	ds_read_b128 v[10:13], v183 offset:64
	ds_read_b128 v[144:147], v183 offset:96
	ds_read_b128 v[148:151], v183 offset:128
	ds_read_b128 v[152:155], v183 offset:160
	ds_read_b128 v[156:159], v183 offset:6656
	ds_read_b128 v[160:163], v183 offset:6688
	ds_read_b128 v[204:207], v183 offset:6720
	ds_read_b128 v[208:211], v183 offset:6752
	ds_read_b128 v[212:215], v183 offset:6784
	ds_read_b128 v[216:219], v183 offset:6816
	s_waitcnt lgkmcnt(11)
	v_mfma_f32_32x32x16_bf16 v[64:79], v[2:5], v[84:87], v[228:243]
	v_add_u32_e32 v2, 0x3000, v185
	s_waitcnt lgkmcnt(5)
	v_mfma_f32_32x32x16_bf16 v[48:63], v[156:159], v[84:87], v[228:243]
	s_cmp_gt_i32 s18, s16
	s_cbranch_scc1 .Lmy_w5_nl
	v_add_u32_e32 v226, 0x8e00, v182
	s_waitcnt vmcnt(9)
	ds_write_b128 v200, v[120:123] offset:23040
	s_waitcnt vmcnt(8)
	ds_write_b128 v201, v[124:127] offset:23040
	s_waitcnt vmcnt(7)
	ds_write_b128 v202, v[132:135] offset:23040
	s_waitcnt vmcnt(6)
	ds_write2_b64 v226, v[136:137], v[138:139] offset1:1
	v_add_u32_e32 v226, 0x8e00, v184
	s_waitcnt vmcnt(5)
	ds_write2_b64 v226, v[140:141], v[142:143] offset1:1
	s_branch .Lmy_w5_dn

; template <int DQK, int MODE> ...
;     ...
;         float rsum = 0.f;
; #pragma unroll
;         for (int ku = 0; ku < 2; ++ku)
; #pragma unroll
;           for (int r = 0; r < 16; ++r) {
;             float e = __builtin_amdgcn_exp2f(S[ku][r]);
;             S[ku][r] = e;
;             rsum += e;
;           }
;         lsum += rsum;
;     ...
; #pragma unroll
;       for (int s = 0; s < 4; ++s) {
;         const int ku = s >> 1, b = 8 * (s & 1);
;         u32x4 t;
;         t.x = pack2(S[ku][b + 0], S[ku][b + 1]);
;         t.y = pack2(S[ku][b + 2], S[ku][b + 3]);
;         t.z = pack2(S[ku][b + 4], S[ku][b + 5]);
;         t.w = pack2(S[ku][b + 6], S[ku][b + 7]);
;         pf[s] = __builtin_bit_cast(bf16x8, t);
;       }
;       if (MODE == 2) {
; #pragma unroll
;         for (int du = 0; du < 2; ++du)
; #pragma unroll
;           for (int s4 = 0; s4 < 4; ++s4) {
;             const u16* vp = Vs + (du * 32 + ql) * VST + 16 * s4 + 4 * hh;
;             u32x2 a = *(const u32x2*)vp;
;             u32x2 b = *(const u32x2*)(vp + 8);
;             vf[du][s4] = (u32x4){a.x, a.y, b.x, b.y};
;           }
;       }
; #pragma unroll
;       for (int s4 = 0; s4 < 4; ++s4)
; #pragma unroll
;         for (int du = 0; du < 2; ++du)
;           O[du] = __builtin_amdgcn_mfma_f32_32x32x16_bf16(__builtin_bit_cast(bf16x8, vf[du][s4]), pf[s4], O[du], 0, 0, 0);
.LBB0_2132:
	s_setprio 1
	v_exp_f32_e32 v14, v64
	v_exp_f32_e32 v64, v65
	v_exp_f32_e32 v65, v66
	v_exp_f32_e32 v66, v67
	v_add_f32_e32 v15, 0, v14
	v_exp_f32_e32 v67, v68
	v_add_f32_e32 v15, v64, v15
	v_exp_f32_e32 v68, v69
	v_add_f32_e32 v15, v65, v15
	v_exp_f32_e32 v69, v70
	v_add_f32_e32 v15, v66, v15
	v_exp_f32_e32 v70, v71
	v_add_f32_e32 v15, v67, v15
	v_exp_f32_e32 v71, v72
	v_add_f32_e32 v15, v68, v15
	v_exp_f32_e32 v72, v73
	v_add_f32_e32 v15, v69, v15
	v_exp_f32_e32 v73, v74
	v_add_f32_e32 v15, v70, v15
	v_exp_f32_e32 v74, v75
	v_exp_f32_e32 v75, v76
	v_exp_f32_e32 v76, v77
	v_exp_f32_e32 v77, v78
	v_exp_f32_e32 v78, v79
	v_exp_f32_e32 v79, v48
	v_exp_f32_e32 v203, v49
	v_exp_f32_e32 v204, v50
	v_exp_f32_e32 v205, v51
	v_cvt_pk_bf16_f32 v48, v14, v64
	v_cvt_pk_bf16_f32 v49, v65, v66
	v_cvt_pk_bf16_f32 v50, v67, v68
	v_cvt_pk_bf16_f32 v51, v69, v70
	v_add_f32_e32 v15, v71, v15
	v_add_f32_e32 v15, v72, v15
	s_waitcnt lgkmcnt(7)
	v_mfma_f32_32x32x16_bf16 v[32:47], v[160:163], v[48:51], v[32:47]
	v_add_f32_e32 v15, v73, v15
	v_add_f32_e32 v15, v74, v15
	v_add_f32_e32 v15, v75, v15
	v_add_f32_e32 v15, v76, v15
	v_add_f32_e32 v15, v77, v15
	v_add_f32_e32 v15, v78, v15
	v_exp_f32_e32 v206, v52
	s_waitcnt lgkmcnt(3)
	v_mfma_f32_32x32x16_bf16 v[16:31], v[156:159], v[48:51], v[16:31]
	v_exp_f32_e32 v207, v53
	v_exp_f32_e32 v208, v54
	v_exp_f32_e32 v209, v55
	v_cvt_pk_bf16_f32 v52, v71, v72
	v_cvt_pk_bf16_f32 v53, v73, v74
	v_cvt_pk_bf16_f32 v54, v75, v76
	v_cvt_pk_bf16_f32 v55, v77, v78
	v_add_f32_e32 v15, v79, v15
	v_add_f32_e32 v15, v203, v15
	v_mfma_f32_32x32x16_bf16 v[32:47], v[152:155], v[52:55], v[32:47]
	v_add_f32_e32 v15, v204, v15
	v_add_f32_e32 v15, v205, v15
	v_add_f32_e32 v15, v206, v15
	v_exp_f32_e32 v210, v56
	v_add_f32_e32 v15, v207, v15
	v_exp_f32_e32 v211, v57
	v_add_f32_e32 v15, v208, v15
	s_waitcnt lgkmcnt(2)
	v_mfma_f32_32x32x16_bf16 v[16:31], v[148:151], v[52:55], v[16:31]
	v_exp_f32_e32 v212, v58
	v_add_f32_e32 v15, v209, v15
	v_exp_f32_e32 v213, v59
	v_cvt_pk_bf16_f32 v56, v79, v203
	v_cvt_pk_bf16_f32 v57, v204, v205
	v_cvt_pk_bf16_f32 v58, v206, v207
	v_cvt_pk_bf16_f32 v59, v208, v209
	v_add_f32_e32 v15, v210, v15
	v_exp_f32_e32 v214, v60
	v_mfma_f32_32x32x16_bf16 v[32:47], v[144:147], v[56:59], v[32:47]
	v_add_f32_e32 v15, v211, v15
	v_exp_f32_e32 v215, v61
	v_add_f32_e32 v15, v212, v15
	v_exp_f32_e32 v216, v62
	v_add_f32_e32 v15, v213, v15
	v_exp_f32_e32 v63, v63
	v_add_f32_e32 v15, v214, v15
	s_waitcnt lgkmcnt(1)
	v_mfma_f32_32x32x16_bf16 v[16:31], v[10:13], v[56:59], v[16:31]
	v_add_f32_e32 v15, v215, v15
	v_add_f32_e32 v15, v216, v15
	v_add_f32_e32 v15, v63, v15
	v_cvt_pk_bf16_f32 v60, v210, v211
	v_cvt_pk_bf16_f32 v61, v212, v213
	v_cvt_pk_bf16_f32 v62, v214, v215
	v_cvt_pk_bf16_f32 v63, v216, v63
	v_add_f32_e32 v175, v175, v15
	s_andn2_b64 s[10:11], s[10:11], exec
	v_mfma_f32_32x32x16_bf16 v[32:47], v[6:9], v[60:63], v[32:47]
	s_waitcnt lgkmcnt(0)
	v_mfma_f32_32x32x16_bf16 v[16:31], v[2:5], v[60:63], v[16:31]
	s_setprio 0
	s_branch .LBB0_2133

; template <int DQK, int MODE> ...
;     ...
;       {
;         bf16x8 kf[2][NKK];
; #pragma unroll
;         for (int ku = 0; ku < 2; ++ku)
; #pragma unroll
;           for (int kk = 0; kk < NKK; ++kk)
;             kf[ku][kk] = *(const bf16x8*)(Ks + (ku * 32 + ql) * KST + kk * 16 + hh * 8);
;         __builtin_amdgcn_sched_barrier(0);
; #pragma unroll
;         for (int ku = 0; ku < 2; ++ku)
; #pragma unroll
;           for (int r = 0; r < 16; ++r) S[ku][r] = cinit;
; #pragma unroll
;         for (int kk = 0; kk < NKK; ++kk)
; #pragma unroll
;           for (int ku = 0; ku < 2; ++ku)
;             S[ku] = __builtin_amdgcn_mfma_f32_32x32x16_bf16(kf[ku][kk], qf[kk], S[ku], 0, 0, 0);
;       }
.LBB0_2136:
	s_and_saveexec_b64 s[14:15], s[30:31]
	s_cbranch_execz .Lmy_ia1_b
	ds_read_b128 v[2:5], v183 offset:23040
	ds_read_b128 v[6:9], v183 offset:23072
	ds_read_b128 v[10:13], v183 offset:23104
	ds_read_b128 v[144:147], v183 offset:23136
	ds_read_b128 v[148:151], v183 offset:23168
	ds_read_b128 v[152:155], v183 offset:23200
	ds_read_b128 v[156:159], v183 offset:29696
	ds_read_b128 v[160:163], v183 offset:29728
	ds_read_b128 v[204:207], v183 offset:29760
	ds_read_b128 v[208:211], v183 offset:29792
	ds_read_b128 v[212:215], v183 offset:29824
	ds_read_b128 v[216:219], v183 offset:29856
	s_waitcnt lgkmcnt(11)
	v_mfma_f32_32x32x16_bf16 v[64:79], v[2:5], v[84:87], v[228:243]
	v_add_u32_e32 v2, 0x8800, v185
	s_waitcnt lgkmcnt(5)
	v_mfma_f32_32x32x16_bf16 v[48:63], v[156:159], v[84:87], v[228:243]
	s_cmp_gt_i32 s17, s16
	s_cbranch_scc1 .Lmy_w6_nl
	v_add_u32_e32 v226, 0x3400, v182
	s_waitcnt vmcnt(9)
	ds_write_b128 v200, v[104:107]
	s_waitcnt vmcnt(8)
	ds_write_b128 v201, v[108:111]
	s_waitcnt vmcnt(7)
	ds_write_b128 v202, v[112:115]
	s_waitcnt vmcnt(6)
	ds_write2_b64 v226, v[116:117], v[118:119] offset1:1
	v_add_u32_e32 v226, 0x3400, v184
	s_waitcnt vmcnt(5)
	ds_write2_b64 v226, v[128:129], v[130:131] offset1:1
	s_branch .Lmy_w6_dn
